# SSD item index permuted (bit fields 0-2 and 3-5 swapped): the eight heads of a B/C group now run on one XCD and share its L2
# speedup vs baseline: 1.0093x; 1.0036x over previous
.LBB0_318:
	s_andn2_b64 vcc, exec, s[0:1]
	s_cbranch_vccnz .LBB0_378
	v_readlane_b32 s0, v254, 59
	v_readlane_b32 s80, v254, 58
	v_readlane_b32 s1, v254, 60
	s_load_dword s0, s[0:1], 0x0
	s_cmpk_gt_i32 s80, 0xff
	s_waitcnt lgkmcnt(0)
	v_writelane_b32 v255, s0, 3
	s_cbranch_scc1 .LBB0_377
	s_and_b32 s30, s80, 0xc0
	s_bfe_u32 s0, s80, 0x30000
	s_lshl_b32 s0, s0, 3
	s_or_b32 s30, s30, s0
	s_bfe_u32 s0, s80, 0x30003
	s_or_b32 s30, s30, s0
	s_mov_b32 s31, s80
	s_branch .LBB0_322
.LBB0_321:
	s_waitcnt lgkmcnt(0)
	s_barrier
	ds_read2st64_b32 v[0:1], v101 offset1:1
	s_waitcnt vmcnt(10)
	ds_read2st64_b32 v[4:5], v101 offset0:2 offset1:3
	v_or_b32_e32 v6, 0xfc0, v56
	v_ashrrev_i32_e32 v7, 31, v6
	v_lshlrev_b64 v[6:7], 5, v[6:7]
	s_waitcnt vmcnt(9) lgkmcnt(1)
	v_mov_b32_e32 v8, v0
	s_waitcnt lgkmcnt(0)
	v_mov_b32_e32 v9, v4
	v_mov_b32_e32 v4, v1
	v_readlane_b32 s0, v252, 44
	v_cndmask_b32_e64 v7, 0, v7, s[40:41]
	v_cndmask_b32_e64 v6, v232, v6, s[40:41]
	v_pk_add_f32 v[0:1], v[8:9], v[4:5]
	v_readlane_b32 s1, v252, 45
	v_add_f32_e32 v2, v0, v1
	v_readlane_b32 s82, v254, 61
	v_lshl_add_u64 v[0:1], v[6:7], 2, s[0:1]
	v_readlane_b32 s0, v255, 3
	s_add_i32 s31, s31, s0
	s_and_b32 s30, s31, 0xc0
	s_bfe_u32 s1, s31, 0x30000
	s_lshl_b32 s1, s1, 3
	s_or_b32 s30, s30, s1
	s_bfe_u32 s1, s31, 0x30003
	s_or_b32 s30, s30, s1
	v_readlane_b32 s56, v254, 63
	v_readlane_b32 s74, v255, 1
	v_lshl_add_u64 v[0:1], v[0:1], 0, s[72:73]
	s_cmpk_gt_i32 s31, 0xff
	v_readlane_b32 s83, v254, 62
	v_readlane_b32 s57, v255, 0
	v_readlane_b32 s75, v255, 2
	s_mov_b32 s67, 0x8000
	s_mov_b64 s[54:55], 0x3000
	s_mov_b64 s[58:59], 0x6000
	global_store_dword v[0:1], v2, off
	s_barrier
	s_cbranch_scc1 .LBB0_377
.LBB0_322:
	s_ashr_i32 s37, s30, 5
	s_and_b32 s36, s30, 31
	v_cmp_gt_u32_e32 vcc, 0x1e0, v197
	s_and_saveexec_b64 s[40:41], vcc
	s_cbranch_execz .LBB0_341
	v_readlane_b32 s16, v254, 50
	v_readlane_b32 s17, v254, 51
	v_readlane_b32 s18, v254, 52
	v_readlane_b32 s19, v254, 53
	s_add_u32 s20, s92, 0x1e380000
	s_addc_u32 s21, s93, 0
	s_lshl_b32 s22, s37, 6
	s_mov_b32 s23, 0xd0000
	s_mov_b32 s42, 0xbfb8aa3b
	s_mov_b32 s43, 0xbfb8aa3b
	s_mov_b32 s44, 0x9000
	s_lshl_b32 s0, s36, 6
	s_lshr_b32 s1, s36, 3
	s_lshl_b32 s1, s1, 7
	s_add_i32 s2, s1, 0x7c0
	s_add_i32 s3, s1, 0x940
	v_mul_u32_u24_e32 v238, 0xcccd, v197
	v_lshrrev_b32_e32 v238, 21, v238
	v_mul_u32_u24_e32 v0, 40, v238
	v_sub_u32_e32 v239, v197, v0
	v_mov_b32_e32 v0, s3
	v_mov_b32_e32 v1, s2
	v_cmp_gt_u32_e32 vcc, 24, v239
	v_mov_b32_e32 v2, s0
	s_nop 1
	v_cndmask_b32_e32 v0, v0, v1, vcc
	v_cmp_gt_u32_e32 vcc, 8, v239
	s_nop 1
	v_cndmask_b32_e32 v0, v0, v2, vcc
	v_lshl_add_u32 v0, v239, 3, v0
	v_lshlrev_b32_e32 v240, 1, v0
	v_lshlrev_b32_e32 v241, 2, v0
	v_add_u32_e32 v242, 0x3000, v241
	v_add_u32_e32 v243, 0x6000, v241
	v_add_u32_e32 v244, 0x9000, v241
	global_load_dwordx4 v[4:7], v241, s[18:19]
	global_load_dwordx4 v[8:11], v241, s[18:19] offset:16
	global_load_dwordx4 v[12:15], v241, s[16:17]
	global_load_dwordx4 v[16:19], v241, s[16:17] offset:16
	global_load_dwordx4 v[20:23], v242, s[16:17]
	global_load_dwordx4 v[24:27], v242, s[16:17] offset:16
	global_load_dwordx4 v[28:31], v243, s[16:17]
	global_load_dwordx4 v[32:35], v243, s[16:17] offset:16
	global_load_dwordx4 v[36:39], v244, s[16:17]
	global_load_dwordx4 v[40:43], v244, s[16:17] offset:16
	v_add_u32_e32 v0, 0, v238
	v_add_u32_e32 v1, s22, v0
	v_add_u32_e32 v2, -1, v1
	v_mad_u32_u24 v1, v1, s44, v240
	v_add_u32_e32 v1, 0x4800, v1
	v_mad_u32_u24 v2, v2, s44, v240
	v_cmp_eq_u32_e32 vcc, 0, v0
	v_add_u32_e32 v0, 0x1580000, v240
	s_nop 0
	v_cndmask_b32_e32 v2, v2, v0, vcc
	global_load_dwordx4 v[44:47], v2, s[20:21]
	v_add_u32_e32 v2, 0x1800, v2
	global_load_dwordx4 v[48:51], v2, s[20:21]
	v_add_u32_e32 v2, 0x1800, v2
	global_load_dwordx4 v[52:55], v2, s[20:21]
	global_load_dwordx4 v[56:59], v1, s[20:21]
	v_add_u32_e32 v1, 0x1800, v1
	global_load_dwordx4 v[60:63], v1, s[20:21]
	v_add_u32_e32 v1, 0x1800, v1
	global_load_dwordx4 v[64:67], v1, s[20:21]
	v_add_u32_e32 v0, 12, v238
	v_add_u32_e32 v1, s22, v0
	v_add_u32_e32 v2, -1, v1
	v_mad_u32_u24 v1, v1, s44, v240
	v_add_u32_e32 v1, 0x4800, v1
	v_mad_u32_u24 v2, v2, s44, v240
	global_load_dwordx4 v[68:71], v2, s[20:21]
	v_add_u32_e32 v2, 0x1800, v2
	global_load_dwordx4 v[72:75], v2, s[20:21]
	v_add_u32_e32 v2, 0x1800, v2
	global_load_dwordx4 v[76:79], v2, s[20:21]
	global_load_dwordx4 v[80:83], v1, s[20:21]
	v_add_u32_e32 v1, 0x1800, v1
	global_load_dwordx4 v[84:87], v1, s[20:21]
	v_add_u32_e32 v1, 0x1800, v1
	global_load_dwordx4 v[88:91], v1, s[20:21]
	v_add_u32_e32 v0, 24, v238
	v_add_u32_e32 v1, s22, v0
	v_add_u32_e32 v2, -1, v1
	v_mad_u32_u24 v1, v1, s44, v240
	v_add_u32_e32 v1, 0x4800, v1
	v_mad_u32_u24 v2, v2, s44, v240
	global_load_dwordx4 v[92:95], v2, s[20:21]
	v_add_u32_e32 v2, 0x1800, v2
	global_load_dwordx4 v[96:99], v2, s[20:21]
	v_add_u32_e32 v2, 0x1800, v2
	global_load_dwordx4 v[100:103], v2, s[20:21]
	global_load_dwordx4 v[104:107], v1, s[20:21]
	v_add_u32_e32 v1, 0x1800, v1
	global_load_dwordx4 v[108:111], v1, s[20:21]
	v_add_u32_e32 v1, 0x1800, v1
	global_load_dwordx4 v[112:115], v1, s[20:21]
	v_add_u32_e32 v0, 36, v238
	v_add_u32_e32 v1, s22, v0
	v_add_u32_e32 v2, -1, v1
	v_mad_u32_u24 v1, v1, s44, v240
	v_add_u32_e32 v1, 0x4800, v1
	v_mad_u32_u24 v2, v2, s44, v240
	global_load_dwordx4 v[116:119], v2, s[20:21]
	v_add_u32_e32 v2, 0x1800, v2
	global_load_dwordx4 v[120:123], v2, s[20:21]
	v_add_u32_e32 v2, 0x1800, v2
	global_load_dwordx4 v[124:127], v2, s[20:21]
	global_load_dwordx4 v[128:131], v1, s[20:21]
	v_add_u32_e32 v1, 0x1800, v1
	global_load_dwordx4 v[132:135], v1, s[20:21]
	v_add_u32_e32 v1, 0x1800, v1
	global_load_dwordx4 v[136:139], v1, s[20:21]
	v_add_u32_e32 v0, 48, v238
	v_add_u32_e32 v1, s22, v0
	v_add_u32_e32 v2, -1, v1
	v_mad_u32_u24 v1, v1, s44, v240
	v_add_u32_e32 v1, 0x4800, v1
	v_mad_u32_u24 v2, v2, s44, v240
	global_load_dwordx4 v[140:143], v2, s[20:21]
	v_add_u32_e32 v2, 0x1800, v2
	global_load_dwordx4 v[144:147], v2, s[20:21]
	v_add_u32_e32 v2, 0x1800, v2
	global_load_dwordx4 v[148:151], v2, s[20:21]
	global_load_dwordx4 v[152:155], v1, s[20:21]
	v_add_u32_e32 v1, 0x1800, v1
	global_load_dwordx4 v[156:159], v1, s[20:21]
	v_add_u32_e32 v1, 0x1800, v1
	global_load_dwordx4 v[160:163], v1, s[20:21]
	v_add_u32_e32 v0, 60, v238
	v_min_u32_e32 v0, 64, v0
	v_cmp_eq_u32_e32 vcc, 64, v0
	v_add_u32_e32 v1, s22, v0
	v_mov_b32_e32 v2, 0x200
	v_cndmask_b32_e32 v1, v1, v2, vcc
	v_add_u32_e32 v2, -1, v1
	v_cndmask_b32_e32 v2, v2, v1, vcc
	v_mad_u32_u24 v1, v1, s44, v240
	v_add_u32_e32 v1, 0x4800, v1
	v_mad_u32_u24 v2, v2, s44, v240
	global_load_dwordx4 v[164:167], v2, s[20:21]
	v_add_u32_e32 v2, 0x1800, v2
	global_load_dwordx4 v[168:171], v2, s[20:21]
	v_add_u32_e32 v2, 0x1800, v2
	global_load_dwordx4 v[172:175], v2, s[20:21]
	global_load_dwordx4 v[176:179], v1, s[20:21]
	v_add_u32_e32 v1, 0x1800, v1
	global_load_dwordx4 v[180:183], v1, s[20:21]
	v_add_u32_e32 v1, 0x1800, v1
	global_load_dwordx4 v[184:187], v1, s[20:21]
	s_waitcnt vmcnt(30)
	v_lshlrev_b32_e32 v202, 16, v44
	v_and_b32_e32 v203, 0xffff0000, v44
	v_lshlrev_b32_e32 v204, 16, v48
	v_and_b32_e32 v205, 0xffff0000, v48
	v_lshlrev_b32_e32 v206, 16, v52
	v_and_b32_e32 v207, 0xffff0000, v52
	v_lshlrev_b32_e32 v208, 16, v56
	v_and_b32_e32 v209, 0xffff0000, v56
	v_lshlrev_b32_e32 v210, 16, v60
	v_and_b32_e32 v211, 0xffff0000, v60
	v_lshlrev_b32_e32 v212, 16, v64
	v_and_b32_e32 v213, 0xffff0000, v64
	v_pk_fma_f32 v[214:215], v[12:13], v[202:203], v[4:5]
	v_pk_fma_f32 v[216:217], v[12:13], v[204:205], v[4:5]
	v_pk_fma_f32 v[236:237], v[12:13], v[206:207], v[4:5]
	v_pk_fma_f32 v[214:215], v[20:21], v[204:205], v[214:215]
	v_pk_fma_f32 v[216:217], v[20:21], v[206:207], v[216:217]
	v_pk_fma_f32 v[236:237], v[20:21], v[208:209], v[236:237]
	v_pk_fma_f32 v[214:215], v[28:29], v[206:207], v[214:215]
	v_pk_fma_f32 v[216:217], v[28:29], v[208:209], v[216:217]
	v_pk_fma_f32 v[236:237], v[28:29], v[210:211], v[236:237]
	v_pk_fma_f32 v[214:215], v[36:37], v[208:209], v[214:215]
	v_pk_fma_f32 v[216:217], v[36:37], v[210:211], v[216:217]
	v_pk_fma_f32 v[236:237], v[36:37], v[212:213], v[236:237]
	v_pk_mul_f32 v[202:203], v[214:215], s[42:43]
	v_pk_mul_f32 v[204:205], v[216:217], s[42:43]
	v_pk_mul_f32 v[206:207], v[236:237], s[42:43]
	v_exp_f32_e32 v202, v202
	v_exp_f32_e32 v203, v203
	v_exp_f32_e32 v204, v204
	v_exp_f32_e32 v205, v205
	v_exp_f32_e32 v206, v206
	v_exp_f32_e32 v207, v207
	s_nop 0
	v_pk_add_f32 v[202:203], v[202:203], 1.0 op_sel_hi:[1,0]
	v_pk_add_f32 v[204:205], v[204:205], 1.0 op_sel_hi:[1,0]
	v_pk_add_f32 v[206:207], v[206:207], 1.0 op_sel_hi:[1,0]
	v_rcp_f32_e32 v202, v202
	v_rcp_f32_e32 v203, v203
	v_rcp_f32_e32 v204, v204
	v_rcp_f32_e32 v205, v205
	v_rcp_f32_e32 v206, v206
	v_rcp_f32_e32 v207, v207
	s_nop 0
	v_pk_mul_f32 v[214:215], v[214:215], v[202:203]
	v_pk_mul_f32 v[216:217], v[216:217], v[204:205]
	v_pk_mul_f32 v[236:237], v[236:237], v[206:207]
	v_cvt_pk_bf16_f32 v44, v214, v215
	v_cvt_pk_bf16_f32 v48, v216, v217
	v_cvt_pk_bf16_f32 v52, v236, v237
	v_lshlrev_b32_e32 v202, 16, v45
	v_and_b32_e32 v203, 0xffff0000, v45
	v_lshlrev_b32_e32 v204, 16, v49
	v_and_b32_e32 v205, 0xffff0000, v49
	v_lshlrev_b32_e32 v206, 16, v53
	v_and_b32_e32 v207, 0xffff0000, v53
	v_lshlrev_b32_e32 v208, 16, v57
	v_and_b32_e32 v209, 0xffff0000, v57
	v_lshlrev_b32_e32 v210, 16, v61
	v_and_b32_e32 v211, 0xffff0000, v61
	v_lshlrev_b32_e32 v212, 16, v65
	v_and_b32_e32 v213, 0xffff0000, v65
	v_pk_fma_f32 v[214:215], v[14:15], v[202:203], v[6:7]
	v_pk_fma_f32 v[216:217], v[14:15], v[204:205], v[6:7]
	v_pk_fma_f32 v[236:237], v[14:15], v[206:207], v[6:7]
	v_pk_fma_f32 v[214:215], v[22:23], v[204:205], v[214:215]
	v_pk_fma_f32 v[216:217], v[22:23], v[206:207], v[216:217]
	v_pk_fma_f32 v[236:237], v[22:23], v[208:209], v[236:237]
	v_pk_fma_f32 v[214:215], v[30:31], v[206:207], v[214:215]
	v_pk_fma_f32 v[216:217], v[30:31], v[208:209], v[216:217]
	v_pk_fma_f32 v[236:237], v[30:31], v[210:211], v[236:237]
	v_pk_fma_f32 v[214:215], v[38:39], v[208:209], v[214:215]
	v_pk_fma_f32 v[216:217], v[38:39], v[210:211], v[216:217]
	v_pk_fma_f32 v[236:237], v[38:39], v[212:213], v[236:237]
	v_pk_mul_f32 v[202:203], v[214:215], s[42:43]
	v_pk_mul_f32 v[204:205], v[216:217], s[42:43]
	v_pk_mul_f32 v[206:207], v[236:237], s[42:43]
	v_exp_f32_e32 v202, v202
	v_exp_f32_e32 v203, v203
	v_exp_f32_e32 v204, v204
	v_exp_f32_e32 v205, v205
	v_exp_f32_e32 v206, v206
	v_exp_f32_e32 v207, v207
	s_nop 0
	v_pk_add_f32 v[202:203], v[202:203], 1.0 op_sel_hi:[1,0]
	v_pk_add_f32 v[204:205], v[204:205], 1.0 op_sel_hi:[1,0]
	v_pk_add_f32 v[206:207], v[206:207], 1.0 op_sel_hi:[1,0]
	v_rcp_f32_e32 v202, v202
	v_rcp_f32_e32 v203, v203
	v_rcp_f32_e32 v204, v204
	v_rcp_f32_e32 v205, v205
	v_rcp_f32_e32 v206, v206
	v_rcp_f32_e32 v207, v207
	s_nop 0
	v_pk_mul_f32 v[214:215], v[214:215], v[202:203]
	v_pk_mul_f32 v[216:217], v[216:217], v[204:205]
	v_pk_mul_f32 v[236:237], v[236:237], v[206:207]
	v_cvt_pk_bf16_f32 v45, v214, v215
	v_cvt_pk_bf16_f32 v49, v216, v217
	v_cvt_pk_bf16_f32 v53, v236, v237
	v_lshlrev_b32_e32 v202, 16, v46
	v_and_b32_e32 v203, 0xffff0000, v46
	v_lshlrev_b32_e32 v204, 16, v50
	v_and_b32_e32 v205, 0xffff0000, v50
	v_lshlrev_b32_e32 v206, 16, v54
	v_and_b32_e32 v207, 0xffff0000, v54
	v_lshlrev_b32_e32 v208, 16, v58
	v_and_b32_e32 v209, 0xffff0000, v58
	v_lshlrev_b32_e32 v210, 16, v62
	v_and_b32_e32 v211, 0xffff0000, v62
	v_lshlrev_b32_e32 v212, 16, v66
	v_and_b32_e32 v213, 0xffff0000, v66
	v_pk_fma_f32 v[214:215], v[16:17], v[202:203], v[8:9]
	v_pk_fma_f32 v[216:217], v[16:17], v[204:205], v[8:9]
	v_pk_fma_f32 v[236:237], v[16:17], v[206:207], v[8:9]
	v_pk_fma_f32 v[214:215], v[24:25], v[204:205], v[214:215]
	v_pk_fma_f32 v[216:217], v[24:25], v[206:207], v[216:217]
	v_pk_fma_f32 v[236:237], v[24:25], v[208:209], v[236:237]
	v_pk_fma_f32 v[214:215], v[32:33], v[206:207], v[214:215]
	v_pk_fma_f32 v[216:217], v[32:33], v[208:209], v[216:217]
	v_pk_fma_f32 v[236:237], v[32:33], v[210:211], v[236:237]
	v_pk_fma_f32 v[214:215], v[40:41], v[208:209], v[214:215]
	v_pk_fma_f32 v[216:217], v[40:41], v[210:211], v[216:217]
	v_pk_fma_f32 v[236:237], v[40:41], v[212:213], v[236:237]
	v_pk_mul_f32 v[202:203], v[214:215], s[42:43]
	v_pk_mul_f32 v[204:205], v[216:217], s[42:43]
	v_pk_mul_f32 v[206:207], v[236:237], s[42:43]
	v_exp_f32_e32 v202, v202
	v_exp_f32_e32 v203, v203
	v_exp_f32_e32 v204, v204
	v_exp_f32_e32 v205, v205
	v_exp_f32_e32 v206, v206
	v_exp_f32_e32 v207, v207
	s_nop 0
	v_pk_add_f32 v[202:203], v[202:203], 1.0 op_sel_hi:[1,0]
	v_pk_add_f32 v[204:205], v[204:205], 1.0 op_sel_hi:[1,0]
	v_pk_add_f32 v[206:207], v[206:207], 1.0 op_sel_hi:[1,0]
	v_rcp_f32_e32 v202, v202
	v_rcp_f32_e32 v203, v203
	v_rcp_f32_e32 v204, v204
	v_rcp_f32_e32 v205, v205
	v_rcp_f32_e32 v206, v206
	v_rcp_f32_e32 v207, v207
	s_nop 0
	v_pk_mul_f32 v[214:215], v[214:215], v[202:203]
	v_pk_mul_f32 v[216:217], v[216:217], v[204:205]
	v_pk_mul_f32 v[236:237], v[236:237], v[206:207]
	v_cvt_pk_bf16_f32 v46, v214, v215
	v_cvt_pk_bf16_f32 v50, v216, v217
	v_cvt_pk_bf16_f32 v54, v236, v237
	v_lshlrev_b32_e32 v202, 16, v47
	v_and_b32_e32 v203, 0xffff0000, v47
	v_lshlrev_b32_e32 v204, 16, v51
	v_and_b32_e32 v205, 0xffff0000, v51
	v_lshlrev_b32_e32 v206, 16, v55
	v_and_b32_e32 v207, 0xffff0000, v55
	v_lshlrev_b32_e32 v208, 16, v59
	v_and_b32_e32 v209, 0xffff0000, v59
	v_lshlrev_b32_e32 v210, 16, v63
	v_and_b32_e32 v211, 0xffff0000, v63
	v_lshlrev_b32_e32 v212, 16, v67
	v_and_b32_e32 v213, 0xffff0000, v67
	v_pk_fma_f32 v[214:215], v[18:19], v[202:203], v[10:11]
	v_pk_fma_f32 v[216:217], v[18:19], v[204:205], v[10:11]
	v_pk_fma_f32 v[236:237], v[18:19], v[206:207], v[10:11]
	v_pk_fma_f32 v[214:215], v[26:27], v[204:205], v[214:215]
	v_pk_fma_f32 v[216:217], v[26:27], v[206:207], v[216:217]
	v_pk_fma_f32 v[236:237], v[26:27], v[208:209], v[236:237]
	v_pk_fma_f32 v[214:215], v[34:35], v[206:207], v[214:215]
	v_pk_fma_f32 v[216:217], v[34:35], v[208:209], v[216:217]
	v_pk_fma_f32 v[236:237], v[34:35], v[210:211], v[236:237]
	v_pk_fma_f32 v[214:215], v[42:43], v[208:209], v[214:215]
	v_pk_fma_f32 v[216:217], v[42:43], v[210:211], v[216:217]
	v_pk_fma_f32 v[236:237], v[42:43], v[212:213], v[236:237]
	v_pk_mul_f32 v[202:203], v[214:215], s[42:43]
	v_pk_mul_f32 v[204:205], v[216:217], s[42:43]
	v_pk_mul_f32 v[206:207], v[236:237], s[42:43]
	v_exp_f32_e32 v202, v202
	v_exp_f32_e32 v203, v203
	v_exp_f32_e32 v204, v204
	v_exp_f32_e32 v205, v205
	v_exp_f32_e32 v206, v206
	v_exp_f32_e32 v207, v207
	s_nop 0
	v_pk_add_f32 v[202:203], v[202:203], 1.0 op_sel_hi:[1,0]
	v_pk_add_f32 v[204:205], v[204:205], 1.0 op_sel_hi:[1,0]
	v_pk_add_f32 v[206:207], v[206:207], 1.0 op_sel_hi:[1,0]
	v_rcp_f32_e32 v202, v202
	v_rcp_f32_e32 v203, v203
	v_rcp_f32_e32 v204, v204
	v_rcp_f32_e32 v205, v205
	v_rcp_f32_e32 v206, v206
	v_rcp_f32_e32 v207, v207
	s_nop 0
	v_pk_mul_f32 v[214:215], v[214:215], v[202:203]
	v_pk_mul_f32 v[216:217], v[216:217], v[204:205]
	v_pk_mul_f32 v[236:237], v[236:237], v[206:207]
	v_cvt_pk_bf16_f32 v47, v214, v215
	v_cvt_pk_bf16_f32 v51, v216, v217
	v_cvt_pk_bf16_f32 v55, v236, v237
	v_add_u32_e32 v0, 0, v238
	v_add_u32_e32 v1, s22, v0
	v_add_u32_e32 v2, 0x1000, v240
	v_mad_u32_u24 v1, v1, s23, v2
	global_store_dwordx4 v1, v[44:47], s[96:97]
	v_add_u32_e32 v1, 0x3400, v1
	global_store_dwordx4 v1, v[48:51], s[96:97]
	v_add_u32_e32 v1, 0x3400, v1
	global_store_dwordx4 v1, v[52:55], s[96:97]
	s_waitcnt vmcnt(27)
	v_lshlrev_b32_e32 v202, 16, v68
	v_and_b32_e32 v203, 0xffff0000, v68
	v_lshlrev_b32_e32 v204, 16, v72
	v_and_b32_e32 v205, 0xffff0000, v72
	v_lshlrev_b32_e32 v206, 16, v76
	v_and_b32_e32 v207, 0xffff0000, v76
	v_lshlrev_b32_e32 v208, 16, v80
	v_and_b32_e32 v209, 0xffff0000, v80
	v_lshlrev_b32_e32 v210, 16, v84
	v_and_b32_e32 v211, 0xffff0000, v84
	v_lshlrev_b32_e32 v212, 16, v88
	v_and_b32_e32 v213, 0xffff0000, v88
	v_pk_fma_f32 v[214:215], v[12:13], v[202:203], v[4:5]
	v_pk_fma_f32 v[216:217], v[12:13], v[204:205], v[4:5]
	v_pk_fma_f32 v[236:237], v[12:13], v[206:207], v[4:5]
	v_pk_fma_f32 v[214:215], v[20:21], v[204:205], v[214:215]
	v_pk_fma_f32 v[216:217], v[20:21], v[206:207], v[216:217]
	v_pk_fma_f32 v[236:237], v[20:21], v[208:209], v[236:237]
	v_pk_fma_f32 v[214:215], v[28:29], v[206:207], v[214:215]
	v_pk_fma_f32 v[216:217], v[28:29], v[208:209], v[216:217]
	v_pk_fma_f32 v[236:237], v[28:29], v[210:211], v[236:237]
	v_pk_fma_f32 v[214:215], v[36:37], v[208:209], v[214:215]
	v_pk_fma_f32 v[216:217], v[36:37], v[210:211], v[216:217]
	v_pk_fma_f32 v[236:237], v[36:37], v[212:213], v[236:237]
	v_pk_mul_f32 v[202:203], v[214:215], s[42:43]
	v_pk_mul_f32 v[204:205], v[216:217], s[42:43]
	v_pk_mul_f32 v[206:207], v[236:237], s[42:43]
	v_exp_f32_e32 v202, v202
	v_exp_f32_e32 v203, v203
	v_exp_f32_e32 v204, v204
	v_exp_f32_e32 v205, v205
	v_exp_f32_e32 v206, v206
	v_exp_f32_e32 v207, v207
	s_nop 0
	v_pk_add_f32 v[202:203], v[202:203], 1.0 op_sel_hi:[1,0]
	v_pk_add_f32 v[204:205], v[204:205], 1.0 op_sel_hi:[1,0]
	v_pk_add_f32 v[206:207], v[206:207], 1.0 op_sel_hi:[1,0]
	v_rcp_f32_e32 v202, v202
	v_rcp_f32_e32 v203, v203
	v_rcp_f32_e32 v204, v204
	v_rcp_f32_e32 v205, v205
	v_rcp_f32_e32 v206, v206
	v_rcp_f32_e32 v207, v207
	s_nop 0
	v_pk_mul_f32 v[214:215], v[214:215], v[202:203]
	v_pk_mul_f32 v[216:217], v[216:217], v[204:205]
	v_pk_mul_f32 v[236:237], v[236:237], v[206:207]
	v_cvt_pk_bf16_f32 v68, v214, v215
	v_cvt_pk_bf16_f32 v72, v216, v217
	v_cvt_pk_bf16_f32 v76, v236, v237
	v_lshlrev_b32_e32 v202, 16, v69
	v_and_b32_e32 v203, 0xffff0000, v69
	v_lshlrev_b32_e32 v204, 16, v73
	v_and_b32_e32 v205, 0xffff0000, v73
	v_lshlrev_b32_e32 v206, 16, v77
	v_and_b32_e32 v207, 0xffff0000, v77
	v_lshlrev_b32_e32 v208, 16, v81
	v_and_b32_e32 v209, 0xffff0000, v81
	v_lshlrev_b32_e32 v210, 16, v85
	v_and_b32_e32 v211, 0xffff0000, v85
	v_lshlrev_b32_e32 v212, 16, v89
	v_and_b32_e32 v213, 0xffff0000, v89
	v_pk_fma_f32 v[214:215], v[14:15], v[202:203], v[6:7]
	v_pk_fma_f32 v[216:217], v[14:15], v[204:205], v[6:7]
	v_pk_fma_f32 v[236:237], v[14:15], v[206:207], v[6:7]
	v_pk_fma_f32 v[214:215], v[22:23], v[204:205], v[214:215]
	v_pk_fma_f32 v[216:217], v[22:23], v[206:207], v[216:217]
	v_pk_fma_f32 v[236:237], v[22:23], v[208:209], v[236:237]
	v_pk_fma_f32 v[214:215], v[30:31], v[206:207], v[214:215]
	v_pk_fma_f32 v[216:217], v[30:31], v[208:209], v[216:217]
	v_pk_fma_f32 v[236:237], v[30:31], v[210:211], v[236:237]
	v_pk_fma_f32 v[214:215], v[38:39], v[208:209], v[214:215]
	v_pk_fma_f32 v[216:217], v[38:39], v[210:211], v[216:217]
	v_pk_fma_f32 v[236:237], v[38:39], v[212:213], v[236:237]
	v_pk_mul_f32 v[202:203], v[214:215], s[42:43]
	v_pk_mul_f32 v[204:205], v[216:217], s[42:43]
	v_pk_mul_f32 v[206:207], v[236:237], s[42:43]
	v_exp_f32_e32 v202, v202
	v_exp_f32_e32 v203, v203
	v_exp_f32_e32 v204, v204
	v_exp_f32_e32 v205, v205
	v_exp_f32_e32 v206, v206
	v_exp_f32_e32 v207, v207
	s_nop 0
	v_pk_add_f32 v[202:203], v[202:203], 1.0 op_sel_hi:[1,0]
	v_pk_add_f32 v[204:205], v[204:205], 1.0 op_sel_hi:[1,0]
	v_pk_add_f32 v[206:207], v[206:207], 1.0 op_sel_hi:[1,0]
	v_rcp_f32_e32 v202, v202
	v_rcp_f32_e32 v203, v203
	v_rcp_f32_e32 v204, v204
	v_rcp_f32_e32 v205, v205
	v_rcp_f32_e32 v206, v206
	v_rcp_f32_e32 v207, v207
	s_nop 0
	v_pk_mul_f32 v[214:215], v[214:215], v[202:203]
	v_pk_mul_f32 v[216:217], v[216:217], v[204:205]
	v_pk_mul_f32 v[236:237], v[236:237], v[206:207]
	v_cvt_pk_bf16_f32 v69, v214, v215
	v_cvt_pk_bf16_f32 v73, v216, v217
	v_cvt_pk_bf16_f32 v77, v236, v237
	v_lshlrev_b32_e32 v202, 16, v70
	v_and_b32_e32 v203, 0xffff0000, v70
	v_lshlrev_b32_e32 v204, 16, v74
	v_and_b32_e32 v205, 0xffff0000, v74
	v_lshlrev_b32_e32 v206, 16, v78
	v_and_b32_e32 v207, 0xffff0000, v78
	v_lshlrev_b32_e32 v208, 16, v82
	v_and_b32_e32 v209, 0xffff0000, v82
	v_lshlrev_b32_e32 v210, 16, v86
	v_and_b32_e32 v211, 0xffff0000, v86
	v_lshlrev_b32_e32 v212, 16, v90
	v_and_b32_e32 v213, 0xffff0000, v90
	v_pk_fma_f32 v[214:215], v[16:17], v[202:203], v[8:9]
	v_pk_fma_f32 v[216:217], v[16:17], v[204:205], v[8:9]
	v_pk_fma_f32 v[236:237], v[16:17], v[206:207], v[8:9]
	v_pk_fma_f32 v[214:215], v[24:25], v[204:205], v[214:215]
	v_pk_fma_f32 v[216:217], v[24:25], v[206:207], v[216:217]
	v_pk_fma_f32 v[236:237], v[24:25], v[208:209], v[236:237]
	v_pk_fma_f32 v[214:215], v[32:33], v[206:207], v[214:215]
	v_pk_fma_f32 v[216:217], v[32:33], v[208:209], v[216:217]
	v_pk_fma_f32 v[236:237], v[32:33], v[210:211], v[236:237]
	v_pk_fma_f32 v[214:215], v[40:41], v[208:209], v[214:215]
	v_pk_fma_f32 v[216:217], v[40:41], v[210:211], v[216:217]
	v_pk_fma_f32 v[236:237], v[40:41], v[212:213], v[236:237]
	v_pk_mul_f32 v[202:203], v[214:215], s[42:43]
	v_pk_mul_f32 v[204:205], v[216:217], s[42:43]
	v_pk_mul_f32 v[206:207], v[236:237], s[42:43]
	v_exp_f32_e32 v202, v202
	v_exp_f32_e32 v203, v203
	v_exp_f32_e32 v204, v204
	v_exp_f32_e32 v205, v205
	v_exp_f32_e32 v206, v206
	v_exp_f32_e32 v207, v207
	s_nop 0
	v_pk_add_f32 v[202:203], v[202:203], 1.0 op_sel_hi:[1,0]
	v_pk_add_f32 v[204:205], v[204:205], 1.0 op_sel_hi:[1,0]
	v_pk_add_f32 v[206:207], v[206:207], 1.0 op_sel_hi:[1,0]
	v_rcp_f32_e32 v202, v202
	v_rcp_f32_e32 v203, v203
	v_rcp_f32_e32 v204, v204
	v_rcp_f32_e32 v205, v205
	v_rcp_f32_e32 v206, v206
	v_rcp_f32_e32 v207, v207
	s_nop 0
	v_pk_mul_f32 v[214:215], v[214:215], v[202:203]
	v_pk_mul_f32 v[216:217], v[216:217], v[204:205]
	v_pk_mul_f32 v[236:237], v[236:237], v[206:207]
	v_cvt_pk_bf16_f32 v70, v214, v215
	v_cvt_pk_bf16_f32 v74, v216, v217
	v_cvt_pk_bf16_f32 v78, v236, v237
	v_lshlrev_b32_e32 v202, 16, v71
	v_and_b32_e32 v203, 0xffff0000, v71
	v_lshlrev_b32_e32 v204, 16, v75
	v_and_b32_e32 v205, 0xffff0000, v75
	v_lshlrev_b32_e32 v206, 16, v79
	v_and_b32_e32 v207, 0xffff0000, v79
	v_lshlrev_b32_e32 v208, 16, v83
	v_and_b32_e32 v209, 0xffff0000, v83
	v_lshlrev_b32_e32 v210, 16, v87
	v_and_b32_e32 v211, 0xffff0000, v87
	v_lshlrev_b32_e32 v212, 16, v91
	v_and_b32_e32 v213, 0xffff0000, v91
	v_pk_fma_f32 v[214:215], v[18:19], v[202:203], v[10:11]
	v_pk_fma_f32 v[216:217], v[18:19], v[204:205], v[10:11]
	v_pk_fma_f32 v[236:237], v[18:19], v[206:207], v[10:11]
	v_pk_fma_f32 v[214:215], v[26:27], v[204:205], v[214:215]
	v_pk_fma_f32 v[216:217], v[26:27], v[206:207], v[216:217]
	v_pk_fma_f32 v[236:237], v[26:27], v[208:209], v[236:237]
	v_pk_fma_f32 v[214:215], v[34:35], v[206:207], v[214:215]
	v_pk_fma_f32 v[216:217], v[34:35], v[208:209], v[216:217]
	v_pk_fma_f32 v[236:237], v[34:35], v[210:211], v[236:237]
	v_pk_fma_f32 v[214:215], v[42:43], v[208:209], v[214:215]
	v_pk_fma_f32 v[216:217], v[42:43], v[210:211], v[216:217]
	v_pk_fma_f32 v[236:237], v[42:43], v[212:213], v[236:237]
	v_pk_mul_f32 v[202:203], v[214:215], s[42:43]
	v_pk_mul_f32 v[204:205], v[216:217], s[42:43]
	v_pk_mul_f32 v[206:207], v[236:237], s[42:43]
	v_exp_f32_e32 v202, v202
	v_exp_f32_e32 v203, v203
	v_exp_f32_e32 v204, v204
	v_exp_f32_e32 v205, v205
	v_exp_f32_e32 v206, v206
	v_exp_f32_e32 v207, v207
	s_nop 0
	v_pk_add_f32 v[202:203], v[202:203], 1.0 op_sel_hi:[1,0]
	v_pk_add_f32 v[204:205], v[204:205], 1.0 op_sel_hi:[1,0]
	v_pk_add_f32 v[206:207], v[206:207], 1.0 op_sel_hi:[1,0]
	v_rcp_f32_e32 v202, v202
	v_rcp_f32_e32 v203, v203
	v_rcp_f32_e32 v204, v204
	v_rcp_f32_e32 v205, v205
	v_rcp_f32_e32 v206, v206
	v_rcp_f32_e32 v207, v207
	s_nop 0
	v_pk_mul_f32 v[214:215], v[214:215], v[202:203]
	v_pk_mul_f32 v[216:217], v[216:217], v[204:205]
	v_pk_mul_f32 v[236:237], v[236:237], v[206:207]
	v_cvt_pk_bf16_f32 v71, v214, v215
	v_cvt_pk_bf16_f32 v75, v216, v217
	v_cvt_pk_bf16_f32 v79, v236, v237
	v_add_u32_e32 v0, 12, v238
	v_add_u32_e32 v1, s22, v0
	v_add_u32_e32 v2, 0x1000, v240
	v_mad_u32_u24 v1, v1, s23, v2
	global_store_dwordx4 v1, v[68:71], s[96:97]
	v_add_u32_e32 v1, 0x3400, v1
	global_store_dwordx4 v1, v[72:75], s[96:97]
	v_add_u32_e32 v1, 0x3400, v1
	global_store_dwordx4 v1, v[76:79], s[96:97]
	s_waitcnt vmcnt(24)
	v_lshlrev_b32_e32 v202, 16, v92
	v_and_b32_e32 v203, 0xffff0000, v92
	v_lshlrev_b32_e32 v204, 16, v96
	v_and_b32_e32 v205, 0xffff0000, v96
	v_lshlrev_b32_e32 v206, 16, v100
	v_and_b32_e32 v207, 0xffff0000, v100
	v_lshlrev_b32_e32 v208, 16, v104
	v_and_b32_e32 v209, 0xffff0000, v104
	v_lshlrev_b32_e32 v210, 16, v108
	v_and_b32_e32 v211, 0xffff0000, v108
	v_lshlrev_b32_e32 v212, 16, v112
	v_and_b32_e32 v213, 0xffff0000, v112
	v_pk_fma_f32 v[214:215], v[12:13], v[202:203], v[4:5]
	v_pk_fma_f32 v[216:217], v[12:13], v[204:205], v[4:5]
	v_pk_fma_f32 v[236:237], v[12:13], v[206:207], v[4:5]
	v_pk_fma_f32 v[214:215], v[20:21], v[204:205], v[214:215]
	v_pk_fma_f32 v[216:217], v[20:21], v[206:207], v[216:217]
	v_pk_fma_f32 v[236:237], v[20:21], v[208:209], v[236:237]
	v_pk_fma_f32 v[214:215], v[28:29], v[206:207], v[214:215]
	v_pk_fma_f32 v[216:217], v[28:29], v[208:209], v[216:217]
	v_pk_fma_f32 v[236:237], v[28:29], v[210:211], v[236:237]
	v_pk_fma_f32 v[214:215], v[36:37], v[208:209], v[214:215]
	v_pk_fma_f32 v[216:217], v[36:37], v[210:211], v[216:217]
	v_pk_fma_f32 v[236:237], v[36:37], v[212:213], v[236:237]
	v_pk_mul_f32 v[202:203], v[214:215], s[42:43]
	v_pk_mul_f32 v[204:205], v[216:217], s[42:43]
	v_pk_mul_f32 v[206:207], v[236:237], s[42:43]
	v_exp_f32_e32 v202, v202
	v_exp_f32_e32 v203, v203
	v_exp_f32_e32 v204, v204
	v_exp_f32_e32 v205, v205
	v_exp_f32_e32 v206, v206
	v_exp_f32_e32 v207, v207
	s_nop 0
	v_pk_add_f32 v[202:203], v[202:203], 1.0 op_sel_hi:[1,0]
	v_pk_add_f32 v[204:205], v[204:205], 1.0 op_sel_hi:[1,0]
	v_pk_add_f32 v[206:207], v[206:207], 1.0 op_sel_hi:[1,0]
	v_rcp_f32_e32 v202, v202
	v_rcp_f32_e32 v203, v203
	v_rcp_f32_e32 v204, v204
	v_rcp_f32_e32 v205, v205
	v_rcp_f32_e32 v206, v206
	v_rcp_f32_e32 v207, v207
	s_nop 0
	v_pk_mul_f32 v[214:215], v[214:215], v[202:203]
	v_pk_mul_f32 v[216:217], v[216:217], v[204:205]
	v_pk_mul_f32 v[236:237], v[236:237], v[206:207]
	v_cvt_pk_bf16_f32 v92, v214, v215
	v_cvt_pk_bf16_f32 v96, v216, v217
	v_cvt_pk_bf16_f32 v100, v236, v237
	v_lshlrev_b32_e32 v202, 16, v93
	v_and_b32_e32 v203, 0xffff0000, v93
	v_lshlrev_b32_e32 v204, 16, v97
	v_and_b32_e32 v205, 0xffff0000, v97
	v_lshlrev_b32_e32 v206, 16, v101
	v_and_b32_e32 v207, 0xffff0000, v101
	v_lshlrev_b32_e32 v208, 16, v105
	v_and_b32_e32 v209, 0xffff0000, v105
	v_lshlrev_b32_e32 v210, 16, v109
	v_and_b32_e32 v211, 0xffff0000, v109
	v_lshlrev_b32_e32 v212, 16, v113
	v_and_b32_e32 v213, 0xffff0000, v113
	v_pk_fma_f32 v[214:215], v[14:15], v[202:203], v[6:7]
	v_pk_fma_f32 v[216:217], v[14:15], v[204:205], v[6:7]
	v_pk_fma_f32 v[236:237], v[14:15], v[206:207], v[6:7]
	v_pk_fma_f32 v[214:215], v[22:23], v[204:205], v[214:215]
	v_pk_fma_f32 v[216:217], v[22:23], v[206:207], v[216:217]
	v_pk_fma_f32 v[236:237], v[22:23], v[208:209], v[236:237]
	v_pk_fma_f32 v[214:215], v[30:31], v[206:207], v[214:215]
	v_pk_fma_f32 v[216:217], v[30:31], v[208:209], v[216:217]
	v_pk_fma_f32 v[236:237], v[30:31], v[210:211], v[236:237]
	v_pk_fma_f32 v[214:215], v[38:39], v[208:209], v[214:215]
	v_pk_fma_f32 v[216:217], v[38:39], v[210:211], v[216:217]
	v_pk_fma_f32 v[236:237], v[38:39], v[212:213], v[236:237]
	v_pk_mul_f32 v[202:203], v[214:215], s[42:43]
	v_pk_mul_f32 v[204:205], v[216:217], s[42:43]
	v_pk_mul_f32 v[206:207], v[236:237], s[42:43]
	v_exp_f32_e32 v202, v202
	v_exp_f32_e32 v203, v203
	v_exp_f32_e32 v204, v204
	v_exp_f32_e32 v205, v205
	v_exp_f32_e32 v206, v206
	v_exp_f32_e32 v207, v207
	s_nop 0
	v_pk_add_f32 v[202:203], v[202:203], 1.0 op_sel_hi:[1,0]
	v_pk_add_f32 v[204:205], v[204:205], 1.0 op_sel_hi:[1,0]
	v_pk_add_f32 v[206:207], v[206:207], 1.0 op_sel_hi:[1,0]
	v_rcp_f32_e32 v202, v202
	v_rcp_f32_e32 v203, v203
	v_rcp_f32_e32 v204, v204
	v_rcp_f32_e32 v205, v205
	v_rcp_f32_e32 v206, v206
	v_rcp_f32_e32 v207, v207
	s_nop 0
	v_pk_mul_f32 v[214:215], v[214:215], v[202:203]
	v_pk_mul_f32 v[216:217], v[216:217], v[204:205]
	v_pk_mul_f32 v[236:237], v[236:237], v[206:207]
	v_cvt_pk_bf16_f32 v93, v214, v215
	v_cvt_pk_bf16_f32 v97, v216, v217
	v_cvt_pk_bf16_f32 v101, v236, v237
	v_lshlrev_b32_e32 v202, 16, v94
	v_and_b32_e32 v203, 0xffff0000, v94
	v_lshlrev_b32_e32 v204, 16, v98
	v_and_b32_e32 v205, 0xffff0000, v98
	v_lshlrev_b32_e32 v206, 16, v102
	v_and_b32_e32 v207, 0xffff0000, v102
	v_lshlrev_b32_e32 v208, 16, v106
	v_and_b32_e32 v209, 0xffff0000, v106
	v_lshlrev_b32_e32 v210, 16, v110
	v_and_b32_e32 v211, 0xffff0000, v110
	v_lshlrev_b32_e32 v212, 16, v114
	v_and_b32_e32 v213, 0xffff0000, v114
	v_pk_fma_f32 v[214:215], v[16:17], v[202:203], v[8:9]
	v_pk_fma_f32 v[216:217], v[16:17], v[204:205], v[8:9]
	v_pk_fma_f32 v[236:237], v[16:17], v[206:207], v[8:9]
	v_pk_fma_f32 v[214:215], v[24:25], v[204:205], v[214:215]
	v_pk_fma_f32 v[216:217], v[24:25], v[206:207], v[216:217]
	v_pk_fma_f32 v[236:237], v[24:25], v[208:209], v[236:237]
	v_pk_fma_f32 v[214:215], v[32:33], v[206:207], v[214:215]
	v_pk_fma_f32 v[216:217], v[32:33], v[208:209], v[216:217]
	v_pk_fma_f32 v[236:237], v[32:33], v[210:211], v[236:237]
	v_pk_fma_f32 v[214:215], v[40:41], v[208:209], v[214:215]
	v_pk_fma_f32 v[216:217], v[40:41], v[210:211], v[216:217]
	v_pk_fma_f32 v[236:237], v[40:41], v[212:213], v[236:237]
	v_pk_mul_f32 v[202:203], v[214:215], s[42:43]
	v_pk_mul_f32 v[204:205], v[216:217], s[42:43]
	v_pk_mul_f32 v[206:207], v[236:237], s[42:43]
	v_exp_f32_e32 v202, v202
	v_exp_f32_e32 v203, v203
	v_exp_f32_e32 v204, v204
	v_exp_f32_e32 v205, v205
	v_exp_f32_e32 v206, v206
	v_exp_f32_e32 v207, v207
	s_nop 0
	v_pk_add_f32 v[202:203], v[202:203], 1.0 op_sel_hi:[1,0]
	v_pk_add_f32 v[204:205], v[204:205], 1.0 op_sel_hi:[1,0]
	v_pk_add_f32 v[206:207], v[206:207], 1.0 op_sel_hi:[1,0]
	v_rcp_f32_e32 v202, v202
	v_rcp_f32_e32 v203, v203
	v_rcp_f32_e32 v204, v204
	v_rcp_f32_e32 v205, v205
	v_rcp_f32_e32 v206, v206
	v_rcp_f32_e32 v207, v207
	s_nop 0
	v_pk_mul_f32 v[214:215], v[214:215], v[202:203]
	v_pk_mul_f32 v[216:217], v[216:217], v[204:205]
	v_pk_mul_f32 v[236:237], v[236:237], v[206:207]
	v_cvt_pk_bf16_f32 v94, v214, v215
	v_cvt_pk_bf16_f32 v98, v216, v217
	v_cvt_pk_bf16_f32 v102, v236, v237
	v_lshlrev_b32_e32 v202, 16, v95
	v_and_b32_e32 v203, 0xffff0000, v95
	v_lshlrev_b32_e32 v204, 16, v99
	v_and_b32_e32 v205, 0xffff0000, v99
	v_lshlrev_b32_e32 v206, 16, v103
	v_and_b32_e32 v207, 0xffff0000, v103
	v_lshlrev_b32_e32 v208, 16, v107
	v_and_b32_e32 v209, 0xffff0000, v107
	v_lshlrev_b32_e32 v210, 16, v111
	v_and_b32_e32 v211, 0xffff0000, v111
	v_lshlrev_b32_e32 v212, 16, v115
	v_and_b32_e32 v213, 0xffff0000, v115
	v_pk_fma_f32 v[214:215], v[18:19], v[202:203], v[10:11]
	v_pk_fma_f32 v[216:217], v[18:19], v[204:205], v[10:11]
	v_pk_fma_f32 v[236:237], v[18:19], v[206:207], v[10:11]
	v_pk_fma_f32 v[214:215], v[26:27], v[204:205], v[214:215]
	v_pk_fma_f32 v[216:217], v[26:27], v[206:207], v[216:217]
	v_pk_fma_f32 v[236:237], v[26:27], v[208:209], v[236:237]
	v_pk_fma_f32 v[214:215], v[34:35], v[206:207], v[214:215]
	v_pk_fma_f32 v[216:217], v[34:35], v[208:209], v[216:217]
	v_pk_fma_f32 v[236:237], v[34:35], v[210:211], v[236:237]
	v_pk_fma_f32 v[214:215], v[42:43], v[208:209], v[214:215]
	v_pk_fma_f32 v[216:217], v[42:43], v[210:211], v[216:217]
	v_pk_fma_f32 v[236:237], v[42:43], v[212:213], v[236:237]
	v_pk_mul_f32 v[202:203], v[214:215], s[42:43]
	v_pk_mul_f32 v[204:205], v[216:217], s[42:43]
	v_pk_mul_f32 v[206:207], v[236:237], s[42:43]
	v_exp_f32_e32 v202, v202
	v_exp_f32_e32 v203, v203
	v_exp_f32_e32 v204, v204
	v_exp_f32_e32 v205, v205
	v_exp_f32_e32 v206, v206
	v_exp_f32_e32 v207, v207
	s_nop 0
	v_pk_add_f32 v[202:203], v[202:203], 1.0 op_sel_hi:[1,0]
	v_pk_add_f32 v[204:205], v[204:205], 1.0 op_sel_hi:[1,0]
	v_pk_add_f32 v[206:207], v[206:207], 1.0 op_sel_hi:[1,0]
	v_rcp_f32_e32 v202, v202
	v_rcp_f32_e32 v203, v203
	v_rcp_f32_e32 v204, v204
	v_rcp_f32_e32 v205, v205
	v_rcp_f32_e32 v206, v206
	v_rcp_f32_e32 v207, v207
	s_nop 0
	v_pk_mul_f32 v[214:215], v[214:215], v[202:203]
	v_pk_mul_f32 v[216:217], v[216:217], v[204:205]
	v_pk_mul_f32 v[236:237], v[236:237], v[206:207]
	v_cvt_pk_bf16_f32 v95, v214, v215
	v_cvt_pk_bf16_f32 v99, v216, v217
	v_cvt_pk_bf16_f32 v103, v236, v237
	v_add_u32_e32 v0, 24, v238
	v_add_u32_e32 v1, s22, v0
	v_add_u32_e32 v2, 0x1000, v240
	v_mad_u32_u24 v1, v1, s23, v2
	global_store_dwordx4 v1, v[92:95], s[96:97]
	v_add_u32_e32 v1, 0x3400, v1
	global_store_dwordx4 v1, v[96:99], s[96:97]
	v_add_u32_e32 v1, 0x3400, v1
	global_store_dwordx4 v1, v[100:103], s[96:97]
	s_waitcnt vmcnt(21)
	v_lshlrev_b32_e32 v202, 16, v116
	v_and_b32_e32 v203, 0xffff0000, v116
	v_lshlrev_b32_e32 v204, 16, v120
	v_and_b32_e32 v205, 0xffff0000, v120
	v_lshlrev_b32_e32 v206, 16, v124
	v_and_b32_e32 v207, 0xffff0000, v124
	v_lshlrev_b32_e32 v208, 16, v128
	v_and_b32_e32 v209, 0xffff0000, v128
	v_lshlrev_b32_e32 v210, 16, v132
	v_and_b32_e32 v211, 0xffff0000, v132
	v_lshlrev_b32_e32 v212, 16, v136
	v_and_b32_e32 v213, 0xffff0000, v136
	v_pk_fma_f32 v[214:215], v[12:13], v[202:203], v[4:5]
	v_pk_fma_f32 v[216:217], v[12:13], v[204:205], v[4:5]
	v_pk_fma_f32 v[236:237], v[12:13], v[206:207], v[4:5]
	v_pk_fma_f32 v[214:215], v[20:21], v[204:205], v[214:215]
	v_pk_fma_f32 v[216:217], v[20:21], v[206:207], v[216:217]
	v_pk_fma_f32 v[236:237], v[20:21], v[208:209], v[236:237]
	v_pk_fma_f32 v[214:215], v[28:29], v[206:207], v[214:215]
	v_pk_fma_f32 v[216:217], v[28:29], v[208:209], v[216:217]
	v_pk_fma_f32 v[236:237], v[28:29], v[210:211], v[236:237]
	v_pk_fma_f32 v[214:215], v[36:37], v[208:209], v[214:215]
	v_pk_fma_f32 v[216:217], v[36:37], v[210:211], v[216:217]
	v_pk_fma_f32 v[236:237], v[36:37], v[212:213], v[236:237]
	v_pk_mul_f32 v[202:203], v[214:215], s[42:43]
	v_pk_mul_f32 v[204:205], v[216:217], s[42:43]
	v_pk_mul_f32 v[206:207], v[236:237], s[42:43]
	v_exp_f32_e32 v202, v202
	v_exp_f32_e32 v203, v203
	v_exp_f32_e32 v204, v204
	v_exp_f32_e32 v205, v205
	v_exp_f32_e32 v206, v206
	v_exp_f32_e32 v207, v207
	s_nop 0
	v_pk_add_f32 v[202:203], v[202:203], 1.0 op_sel_hi:[1,0]
	v_pk_add_f32 v[204:205], v[204:205], 1.0 op_sel_hi:[1,0]
	v_pk_add_f32 v[206:207], v[206:207], 1.0 op_sel_hi:[1,0]
	v_rcp_f32_e32 v202, v202
	v_rcp_f32_e32 v203, v203
	v_rcp_f32_e32 v204, v204
	v_rcp_f32_e32 v205, v205
	v_rcp_f32_e32 v206, v206
	v_rcp_f32_e32 v207, v207
	s_nop 0
	v_pk_mul_f32 v[214:215], v[214:215], v[202:203]
	v_pk_mul_f32 v[216:217], v[216:217], v[204:205]
	v_pk_mul_f32 v[236:237], v[236:237], v[206:207]
	v_cvt_pk_bf16_f32 v116, v214, v215
	v_cvt_pk_bf16_f32 v120, v216, v217
	v_cvt_pk_bf16_f32 v124, v236, v237
	v_lshlrev_b32_e32 v202, 16, v117
	v_and_b32_e32 v203, 0xffff0000, v117
	v_lshlrev_b32_e32 v204, 16, v121
	v_and_b32_e32 v205, 0xffff0000, v121
	v_lshlrev_b32_e32 v206, 16, v125
	v_and_b32_e32 v207, 0xffff0000, v125
	v_lshlrev_b32_e32 v208, 16, v129
	v_and_b32_e32 v209, 0xffff0000, v129
	v_lshlrev_b32_e32 v210, 16, v133
	v_and_b32_e32 v211, 0xffff0000, v133
	v_lshlrev_b32_e32 v212, 16, v137
	v_and_b32_e32 v213, 0xffff0000, v137
	v_pk_fma_f32 v[214:215], v[14:15], v[202:203], v[6:7]
	v_pk_fma_f32 v[216:217], v[14:15], v[204:205], v[6:7]
	v_pk_fma_f32 v[236:237], v[14:15], v[206:207], v[6:7]
	v_pk_fma_f32 v[214:215], v[22:23], v[204:205], v[214:215]
	v_pk_fma_f32 v[216:217], v[22:23], v[206:207], v[216:217]
	v_pk_fma_f32 v[236:237], v[22:23], v[208:209], v[236:237]
	v_pk_fma_f32 v[214:215], v[30:31], v[206:207], v[214:215]
	v_pk_fma_f32 v[216:217], v[30:31], v[208:209], v[216:217]
	v_pk_fma_f32 v[236:237], v[30:31], v[210:211], v[236:237]
	v_pk_fma_f32 v[214:215], v[38:39], v[208:209], v[214:215]
	v_pk_fma_f32 v[216:217], v[38:39], v[210:211], v[216:217]
	v_pk_fma_f32 v[236:237], v[38:39], v[212:213], v[236:237]
	v_pk_mul_f32 v[202:203], v[214:215], s[42:43]
	v_pk_mul_f32 v[204:205], v[216:217], s[42:43]
	v_pk_mul_f32 v[206:207], v[236:237], s[42:43]
	v_exp_f32_e32 v202, v202
	v_exp_f32_e32 v203, v203
	v_exp_f32_e32 v204, v204
	v_exp_f32_e32 v205, v205
	v_exp_f32_e32 v206, v206
	v_exp_f32_e32 v207, v207
	s_nop 0
	v_pk_add_f32 v[202:203], v[202:203], 1.0 op_sel_hi:[1,0]
	v_pk_add_f32 v[204:205], v[204:205], 1.0 op_sel_hi:[1,0]
	v_pk_add_f32 v[206:207], v[206:207], 1.0 op_sel_hi:[1,0]
	v_rcp_f32_e32 v202, v202
	v_rcp_f32_e32 v203, v203
	v_rcp_f32_e32 v204, v204
	v_rcp_f32_e32 v205, v205
	v_rcp_f32_e32 v206, v206
	v_rcp_f32_e32 v207, v207
	s_nop 0
	v_pk_mul_f32 v[214:215], v[214:215], v[202:203]
	v_pk_mul_f32 v[216:217], v[216:217], v[204:205]
	v_pk_mul_f32 v[236:237], v[236:237], v[206:207]
	v_cvt_pk_bf16_f32 v117, v214, v215
	v_cvt_pk_bf16_f32 v121, v216, v217
	v_cvt_pk_bf16_f32 v125, v236, v237
	v_lshlrev_b32_e32 v202, 16, v118
	v_and_b32_e32 v203, 0xffff0000, v118
	v_lshlrev_b32_e32 v204, 16, v122
	v_and_b32_e32 v205, 0xffff0000, v122
	v_lshlrev_b32_e32 v206, 16, v126
	v_and_b32_e32 v207, 0xffff0000, v126
	v_lshlrev_b32_e32 v208, 16, v130
	v_and_b32_e32 v209, 0xffff0000, v130
	v_lshlrev_b32_e32 v210, 16, v134
	v_and_b32_e32 v211, 0xffff0000, v134
	v_lshlrev_b32_e32 v212, 16, v138
	v_and_b32_e32 v213, 0xffff0000, v138
	v_pk_fma_f32 v[214:215], v[16:17], v[202:203], v[8:9]
	v_pk_fma_f32 v[216:217], v[16:17], v[204:205], v[8:9]
	v_pk_fma_f32 v[236:237], v[16:17], v[206:207], v[8:9]
	v_pk_fma_f32 v[214:215], v[24:25], v[204:205], v[214:215]
	v_pk_fma_f32 v[216:217], v[24:25], v[206:207], v[216:217]
	v_pk_fma_f32 v[236:237], v[24:25], v[208:209], v[236:237]
	v_pk_fma_f32 v[214:215], v[32:33], v[206:207], v[214:215]
	v_pk_fma_f32 v[216:217], v[32:33], v[208:209], v[216:217]
	v_pk_fma_f32 v[236:237], v[32:33], v[210:211], v[236:237]
	v_pk_fma_f32 v[214:215], v[40:41], v[208:209], v[214:215]
	v_pk_fma_f32 v[216:217], v[40:41], v[210:211], v[216:217]
	v_pk_fma_f32 v[236:237], v[40:41], v[212:213], v[236:237]
	v_pk_mul_f32 v[202:203], v[214:215], s[42:43]
	v_pk_mul_f32 v[204:205], v[216:217], s[42:43]
	v_pk_mul_f32 v[206:207], v[236:237], s[42:43]
	v_exp_f32_e32 v202, v202
	v_exp_f32_e32 v203, v203
	v_exp_f32_e32 v204, v204
	v_exp_f32_e32 v205, v205
	v_exp_f32_e32 v206, v206
	v_exp_f32_e32 v207, v207
	s_nop 0
	v_pk_add_f32 v[202:203], v[202:203], 1.0 op_sel_hi:[1,0]
	v_pk_add_f32 v[204:205], v[204:205], 1.0 op_sel_hi:[1,0]
	v_pk_add_f32 v[206:207], v[206:207], 1.0 op_sel_hi:[1,0]
	v_rcp_f32_e32 v202, v202
	v_rcp_f32_e32 v203, v203
	v_rcp_f32_e32 v204, v204
	v_rcp_f32_e32 v205, v205
	v_rcp_f32_e32 v206, v206
	v_rcp_f32_e32 v207, v207
	s_nop 0
	v_pk_mul_f32 v[214:215], v[214:215], v[202:203]
	v_pk_mul_f32 v[216:217], v[216:217], v[204:205]
	v_pk_mul_f32 v[236:237], v[236:237], v[206:207]
	v_cvt_pk_bf16_f32 v118, v214, v215
	v_cvt_pk_bf16_f32 v122, v216, v217
	v_cvt_pk_bf16_f32 v126, v236, v237
	v_lshlrev_b32_e32 v202, 16, v119
	v_and_b32_e32 v203, 0xffff0000, v119
	v_lshlrev_b32_e32 v204, 16, v123
	v_and_b32_e32 v205, 0xffff0000, v123
	v_lshlrev_b32_e32 v206, 16, v127
	v_and_b32_e32 v207, 0xffff0000, v127
	v_lshlrev_b32_e32 v208, 16, v131
	v_and_b32_e32 v209, 0xffff0000, v131
	v_lshlrev_b32_e32 v210, 16, v135
	v_and_b32_e32 v211, 0xffff0000, v135
	v_lshlrev_b32_e32 v212, 16, v139
	v_and_b32_e32 v213, 0xffff0000, v139
	v_pk_fma_f32 v[214:215], v[18:19], v[202:203], v[10:11]
	v_pk_fma_f32 v[216:217], v[18:19], v[204:205], v[10:11]
	v_pk_fma_f32 v[236:237], v[18:19], v[206:207], v[10:11]
	v_pk_fma_f32 v[214:215], v[26:27], v[204:205], v[214:215]
	v_pk_fma_f32 v[216:217], v[26:27], v[206:207], v[216:217]
	v_pk_fma_f32 v[236:237], v[26:27], v[208:209], v[236:237]
	v_pk_fma_f32 v[214:215], v[34:35], v[206:207], v[214:215]
	v_pk_fma_f32 v[216:217], v[34:35], v[208:209], v[216:217]
	v_pk_fma_f32 v[236:237], v[34:35], v[210:211], v[236:237]
	v_pk_fma_f32 v[214:215], v[42:43], v[208:209], v[214:215]
	v_pk_fma_f32 v[216:217], v[42:43], v[210:211], v[216:217]
	v_pk_fma_f32 v[236:237], v[42:43], v[212:213], v[236:237]
	v_pk_mul_f32 v[202:203], v[214:215], s[42:43]
	v_pk_mul_f32 v[204:205], v[216:217], s[42:43]
	v_pk_mul_f32 v[206:207], v[236:237], s[42:43]
	v_exp_f32_e32 v202, v202
	v_exp_f32_e32 v203, v203
	v_exp_f32_e32 v204, v204
	v_exp_f32_e32 v205, v205
	v_exp_f32_e32 v206, v206
	v_exp_f32_e32 v207, v207
	s_nop 0
	v_pk_add_f32 v[202:203], v[202:203], 1.0 op_sel_hi:[1,0]
	v_pk_add_f32 v[204:205], v[204:205], 1.0 op_sel_hi:[1,0]
	v_pk_add_f32 v[206:207], v[206:207], 1.0 op_sel_hi:[1,0]
	v_rcp_f32_e32 v202, v202
	v_rcp_f32_e32 v203, v203
	v_rcp_f32_e32 v204, v204
	v_rcp_f32_e32 v205, v205
	v_rcp_f32_e32 v206, v206
	v_rcp_f32_e32 v207, v207
	s_nop 0
	v_pk_mul_f32 v[214:215], v[214:215], v[202:203]
	v_pk_mul_f32 v[216:217], v[216:217], v[204:205]
	v_pk_mul_f32 v[236:237], v[236:237], v[206:207]
	v_cvt_pk_bf16_f32 v119, v214, v215
	v_cvt_pk_bf16_f32 v123, v216, v217
	v_cvt_pk_bf16_f32 v127, v236, v237
	v_add_u32_e32 v0, 36, v238
	v_add_u32_e32 v1, s22, v0
	v_add_u32_e32 v2, 0x1000, v240
	v_mad_u32_u24 v1, v1, s23, v2
	global_store_dwordx4 v1, v[116:119], s[96:97]
	v_add_u32_e32 v1, 0x3400, v1
	global_store_dwordx4 v1, v[120:123], s[96:97]
	v_add_u32_e32 v1, 0x3400, v1
	global_store_dwordx4 v1, v[124:127], s[96:97]
	s_waitcnt vmcnt(18)
	v_lshlrev_b32_e32 v202, 16, v140
	v_and_b32_e32 v203, 0xffff0000, v140
	v_lshlrev_b32_e32 v204, 16, v144
	v_and_b32_e32 v205, 0xffff0000, v144
	v_lshlrev_b32_e32 v206, 16, v148
	v_and_b32_e32 v207, 0xffff0000, v148
	v_lshlrev_b32_e32 v208, 16, v152
	v_and_b32_e32 v209, 0xffff0000, v152
	v_lshlrev_b32_e32 v210, 16, v156
	v_and_b32_e32 v211, 0xffff0000, v156
	v_lshlrev_b32_e32 v212, 16, v160
	v_and_b32_e32 v213, 0xffff0000, v160
	v_pk_fma_f32 v[214:215], v[12:13], v[202:203], v[4:5]
	v_pk_fma_f32 v[216:217], v[12:13], v[204:205], v[4:5]
	v_pk_fma_f32 v[236:237], v[12:13], v[206:207], v[4:5]
	v_pk_fma_f32 v[214:215], v[20:21], v[204:205], v[214:215]
	v_pk_fma_f32 v[216:217], v[20:21], v[206:207], v[216:217]
	v_pk_fma_f32 v[236:237], v[20:21], v[208:209], v[236:237]
	v_pk_fma_f32 v[214:215], v[28:29], v[206:207], v[214:215]
	v_pk_fma_f32 v[216:217], v[28:29], v[208:209], v[216:217]
	v_pk_fma_f32 v[236:237], v[28:29], v[210:211], v[236:237]
	v_pk_fma_f32 v[214:215], v[36:37], v[208:209], v[214:215]
	v_pk_fma_f32 v[216:217], v[36:37], v[210:211], v[216:217]
	v_pk_fma_f32 v[236:237], v[36:37], v[212:213], v[236:237]
	v_pk_mul_f32 v[202:203], v[214:215], s[42:43]
	v_pk_mul_f32 v[204:205], v[216:217], s[42:43]
	v_pk_mul_f32 v[206:207], v[236:237], s[42:43]
	v_exp_f32_e32 v202, v202
	v_exp_f32_e32 v203, v203
	v_exp_f32_e32 v204, v204
	v_exp_f32_e32 v205, v205
	v_exp_f32_e32 v206, v206
	v_exp_f32_e32 v207, v207
	s_nop 0
	v_pk_add_f32 v[202:203], v[202:203], 1.0 op_sel_hi:[1,0]
	v_pk_add_f32 v[204:205], v[204:205], 1.0 op_sel_hi:[1,0]
	v_pk_add_f32 v[206:207], v[206:207], 1.0 op_sel_hi:[1,0]
	v_rcp_f32_e32 v202, v202
	v_rcp_f32_e32 v203, v203
	v_rcp_f32_e32 v204, v204
	v_rcp_f32_e32 v205, v205
	v_rcp_f32_e32 v206, v206
	v_rcp_f32_e32 v207, v207
	s_nop 0
	v_pk_mul_f32 v[214:215], v[214:215], v[202:203]
	v_pk_mul_f32 v[216:217], v[216:217], v[204:205]
	v_pk_mul_f32 v[236:237], v[236:237], v[206:207]
	v_cvt_pk_bf16_f32 v140, v214, v215
	v_cvt_pk_bf16_f32 v144, v216, v217
	v_cvt_pk_bf16_f32 v148, v236, v237
	v_lshlrev_b32_e32 v202, 16, v141
	v_and_b32_e32 v203, 0xffff0000, v141
	v_lshlrev_b32_e32 v204, 16, v145
	v_and_b32_e32 v205, 0xffff0000, v145
	v_lshlrev_b32_e32 v206, 16, v149
	v_and_b32_e32 v207, 0xffff0000, v149
	v_lshlrev_b32_e32 v208, 16, v153
	v_and_b32_e32 v209, 0xffff0000, v153
	v_lshlrev_b32_e32 v210, 16, v157
	v_and_b32_e32 v211, 0xffff0000, v157
	v_lshlrev_b32_e32 v212, 16, v161
	v_and_b32_e32 v213, 0xffff0000, v161
	v_pk_fma_f32 v[214:215], v[14:15], v[202:203], v[6:7]
	v_pk_fma_f32 v[216:217], v[14:15], v[204:205], v[6:7]
	v_pk_fma_f32 v[236:237], v[14:15], v[206:207], v[6:7]
	v_pk_fma_f32 v[214:215], v[22:23], v[204:205], v[214:215]
	v_pk_fma_f32 v[216:217], v[22:23], v[206:207], v[216:217]
	v_pk_fma_f32 v[236:237], v[22:23], v[208:209], v[236:237]
	v_pk_fma_f32 v[214:215], v[30:31], v[206:207], v[214:215]
	v_pk_fma_f32 v[216:217], v[30:31], v[208:209], v[216:217]
	v_pk_fma_f32 v[236:237], v[30:31], v[210:211], v[236:237]
	v_pk_fma_f32 v[214:215], v[38:39], v[208:209], v[214:215]
	v_pk_fma_f32 v[216:217], v[38:39], v[210:211], v[216:217]
	v_pk_fma_f32 v[236:237], v[38:39], v[212:213], v[236:237]
	v_pk_mul_f32 v[202:203], v[214:215], s[42:43]
	v_pk_mul_f32 v[204:205], v[216:217], s[42:43]
	v_pk_mul_f32 v[206:207], v[236:237], s[42:43]
	v_exp_f32_e32 v202, v202
	v_exp_f32_e32 v203, v203
	v_exp_f32_e32 v204, v204
	v_exp_f32_e32 v205, v205
	v_exp_f32_e32 v206, v206
	v_exp_f32_e32 v207, v207
	s_nop 0
	v_pk_add_f32 v[202:203], v[202:203], 1.0 op_sel_hi:[1,0]
	v_pk_add_f32 v[204:205], v[204:205], 1.0 op_sel_hi:[1,0]
	v_pk_add_f32 v[206:207], v[206:207], 1.0 op_sel_hi:[1,0]
	v_rcp_f32_e32 v202, v202
	v_rcp_f32_e32 v203, v203
	v_rcp_f32_e32 v204, v204
	v_rcp_f32_e32 v205, v205
	v_rcp_f32_e32 v206, v206
	v_rcp_f32_e32 v207, v207
	s_nop 0
	v_pk_mul_f32 v[214:215], v[214:215], v[202:203]
	v_pk_mul_f32 v[216:217], v[216:217], v[204:205]
	v_pk_mul_f32 v[236:237], v[236:237], v[206:207]
	v_cvt_pk_bf16_f32 v141, v214, v215
	v_cvt_pk_bf16_f32 v145, v216, v217
	v_cvt_pk_bf16_f32 v149, v236, v237
	v_lshlrev_b32_e32 v202, 16, v142
	v_and_b32_e32 v203, 0xffff0000, v142
	v_lshlrev_b32_e32 v204, 16, v146
	v_and_b32_e32 v205, 0xffff0000, v146
	v_lshlrev_b32_e32 v206, 16, v150
	v_and_b32_e32 v207, 0xffff0000, v150
	v_lshlrev_b32_e32 v208, 16, v154
	v_and_b32_e32 v209, 0xffff0000, v154
	v_lshlrev_b32_e32 v210, 16, v158
	v_and_b32_e32 v211, 0xffff0000, v158
	v_lshlrev_b32_e32 v212, 16, v162
	v_and_b32_e32 v213, 0xffff0000, v162
	v_pk_fma_f32 v[214:215], v[16:17], v[202:203], v[8:9]
	v_pk_fma_f32 v[216:217], v[16:17], v[204:205], v[8:9]
	v_pk_fma_f32 v[236:237], v[16:17], v[206:207], v[8:9]
	v_pk_fma_f32 v[214:215], v[24:25], v[204:205], v[214:215]
	v_pk_fma_f32 v[216:217], v[24:25], v[206:207], v[216:217]
	v_pk_fma_f32 v[236:237], v[24:25], v[208:209], v[236:237]
	v_pk_fma_f32 v[214:215], v[32:33], v[206:207], v[214:215]
	v_pk_fma_f32 v[216:217], v[32:33], v[208:209], v[216:217]
	v_pk_fma_f32 v[236:237], v[32:33], v[210:211], v[236:237]
	v_pk_fma_f32 v[214:215], v[40:41], v[208:209], v[214:215]
	v_pk_fma_f32 v[216:217], v[40:41], v[210:211], v[216:217]
	v_pk_fma_f32 v[236:237], v[40:41], v[212:213], v[236:237]
	v_pk_mul_f32 v[202:203], v[214:215], s[42:43]
	v_pk_mul_f32 v[204:205], v[216:217], s[42:43]
	v_pk_mul_f32 v[206:207], v[236:237], s[42:43]
	v_exp_f32_e32 v202, v202
	v_exp_f32_e32 v203, v203
	v_exp_f32_e32 v204, v204
	v_exp_f32_e32 v205, v205
	v_exp_f32_e32 v206, v206
	v_exp_f32_e32 v207, v207
	s_nop 0
	v_pk_add_f32 v[202:203], v[202:203], 1.0 op_sel_hi:[1,0]
	v_pk_add_f32 v[204:205], v[204:205], 1.0 op_sel_hi:[1,0]
	v_pk_add_f32 v[206:207], v[206:207], 1.0 op_sel_hi:[1,0]
	v_rcp_f32_e32 v202, v202
	v_rcp_f32_e32 v203, v203
	v_rcp_f32_e32 v204, v204
	v_rcp_f32_e32 v205, v205
	v_rcp_f32_e32 v206, v206
	v_rcp_f32_e32 v207, v207
	s_nop 0
	v_pk_mul_f32 v[214:215], v[214:215], v[202:203]
	v_pk_mul_f32 v[216:217], v[216:217], v[204:205]
	v_pk_mul_f32 v[236:237], v[236:237], v[206:207]
	v_cvt_pk_bf16_f32 v142, v214, v215
	v_cvt_pk_bf16_f32 v146, v216, v217
	v_cvt_pk_bf16_f32 v150, v236, v237
	v_lshlrev_b32_e32 v202, 16, v143
	v_and_b32_e32 v203, 0xffff0000, v143
	v_lshlrev_b32_e32 v204, 16, v147
	v_and_b32_e32 v205, 0xffff0000, v147
	v_lshlrev_b32_e32 v206, 16, v151
	v_and_b32_e32 v207, 0xffff0000, v151
	v_lshlrev_b32_e32 v208, 16, v155
	v_and_b32_e32 v209, 0xffff0000, v155
	v_lshlrev_b32_e32 v210, 16, v159
	v_and_b32_e32 v211, 0xffff0000, v159
	v_lshlrev_b32_e32 v212, 16, v163
	v_and_b32_e32 v213, 0xffff0000, v163
	v_pk_fma_f32 v[214:215], v[18:19], v[202:203], v[10:11]
	v_pk_fma_f32 v[216:217], v[18:19], v[204:205], v[10:11]
	v_pk_fma_f32 v[236:237], v[18:19], v[206:207], v[10:11]
	v_pk_fma_f32 v[214:215], v[26:27], v[204:205], v[214:215]
	v_pk_fma_f32 v[216:217], v[26:27], v[206:207], v[216:217]
	v_pk_fma_f32 v[236:237], v[26:27], v[208:209], v[236:237]
	v_pk_fma_f32 v[214:215], v[34:35], v[206:207], v[214:215]
	v_pk_fma_f32 v[216:217], v[34:35], v[208:209], v[216:217]
	v_pk_fma_f32 v[236:237], v[34:35], v[210:211], v[236:237]
	v_pk_fma_f32 v[214:215], v[42:43], v[208:209], v[214:215]
	v_pk_fma_f32 v[216:217], v[42:43], v[210:211], v[216:217]
	v_pk_fma_f32 v[236:237], v[42:43], v[212:213], v[236:237]
	v_pk_mul_f32 v[202:203], v[214:215], s[42:43]
	v_pk_mul_f32 v[204:205], v[216:217], s[42:43]
	v_pk_mul_f32 v[206:207], v[236:237], s[42:43]
	v_exp_f32_e32 v202, v202
	v_exp_f32_e32 v203, v203
	v_exp_f32_e32 v204, v204
	v_exp_f32_e32 v205, v205
	v_exp_f32_e32 v206, v206
	v_exp_f32_e32 v207, v207
	s_nop 0
	v_pk_add_f32 v[202:203], v[202:203], 1.0 op_sel_hi:[1,0]
	v_pk_add_f32 v[204:205], v[204:205], 1.0 op_sel_hi:[1,0]
	v_pk_add_f32 v[206:207], v[206:207], 1.0 op_sel_hi:[1,0]
	v_rcp_f32_e32 v202, v202
	v_rcp_f32_e32 v203, v203
	v_rcp_f32_e32 v204, v204
	v_rcp_f32_e32 v205, v205
	v_rcp_f32_e32 v206, v206
	v_rcp_f32_e32 v207, v207
	s_nop 0
	v_pk_mul_f32 v[214:215], v[214:215], v[202:203]
	v_pk_mul_f32 v[216:217], v[216:217], v[204:205]
	v_pk_mul_f32 v[236:237], v[236:237], v[206:207]
	v_cvt_pk_bf16_f32 v143, v214, v215
	v_cvt_pk_bf16_f32 v147, v216, v217
	v_cvt_pk_bf16_f32 v151, v236, v237
	v_add_u32_e32 v0, 48, v238
	v_add_u32_e32 v1, s22, v0
	v_add_u32_e32 v2, 0x1000, v240
	v_mad_u32_u24 v1, v1, s23, v2
	global_store_dwordx4 v1, v[140:143], s[96:97]
	v_add_u32_e32 v1, 0x3400, v1
	global_store_dwordx4 v1, v[144:147], s[96:97]
	v_add_u32_e32 v1, 0x3400, v1
	global_store_dwordx4 v1, v[148:151], s[96:97]
	s_waitcnt vmcnt(15)
	v_add_u32_e32 v0, 60, v238
	v_cmp_eq_u32_e32 vcc, 64, v0
	s_nop 1
	v_cndmask_b32_e32 v164, v164, v3, vcc
	v_cndmask_b32_e32 v165, v165, v3, vcc
	v_cndmask_b32_e32 v166, v166, v3, vcc
	v_cndmask_b32_e32 v167, v167, v3, vcc
	v_cndmask_b32_e32 v168, v168, v3, vcc
	v_cndmask_b32_e32 v169, v169, v3, vcc
	v_cndmask_b32_e32 v170, v170, v3, vcc
	v_cndmask_b32_e32 v171, v171, v3, vcc
	v_cndmask_b32_e32 v172, v172, v3, vcc
	v_cndmask_b32_e32 v173, v173, v3, vcc
	v_cndmask_b32_e32 v174, v174, v3, vcc
	v_cndmask_b32_e32 v175, v175, v3, vcc
	v_lshlrev_b32_e32 v202, 16, v164
	v_and_b32_e32 v203, 0xffff0000, v164
	v_lshlrev_b32_e32 v204, 16, v168
	v_and_b32_e32 v205, 0xffff0000, v168
	v_lshlrev_b32_e32 v206, 16, v172
	v_and_b32_e32 v207, 0xffff0000, v172
	v_lshlrev_b32_e32 v208, 16, v176
	v_and_b32_e32 v209, 0xffff0000, v176
	v_lshlrev_b32_e32 v210, 16, v180
	v_and_b32_e32 v211, 0xffff0000, v180
	v_lshlrev_b32_e32 v212, 16, v184
	v_and_b32_e32 v213, 0xffff0000, v184
	v_pk_fma_f32 v[214:215], v[12:13], v[202:203], v[4:5]
	v_pk_fma_f32 v[216:217], v[12:13], v[204:205], v[4:5]
	v_pk_fma_f32 v[236:237], v[12:13], v[206:207], v[4:5]
	v_pk_fma_f32 v[214:215], v[20:21], v[204:205], v[214:215]
	v_pk_fma_f32 v[216:217], v[20:21], v[206:207], v[216:217]
	v_pk_fma_f32 v[236:237], v[20:21], v[208:209], v[236:237]
	v_pk_fma_f32 v[214:215], v[28:29], v[206:207], v[214:215]
	v_pk_fma_f32 v[216:217], v[28:29], v[208:209], v[216:217]
	v_pk_fma_f32 v[236:237], v[28:29], v[210:211], v[236:237]
	v_pk_fma_f32 v[214:215], v[36:37], v[208:209], v[214:215]
	v_pk_fma_f32 v[216:217], v[36:37], v[210:211], v[216:217]
	v_pk_fma_f32 v[236:237], v[36:37], v[212:213], v[236:237]
	v_pk_mul_f32 v[202:203], v[214:215], s[42:43]
	v_pk_mul_f32 v[204:205], v[216:217], s[42:43]
	v_pk_mul_f32 v[206:207], v[236:237], s[42:43]
	v_exp_f32_e32 v202, v202
	v_exp_f32_e32 v203, v203
	v_exp_f32_e32 v204, v204
	v_exp_f32_e32 v205, v205
	v_exp_f32_e32 v206, v206
	v_exp_f32_e32 v207, v207
	s_nop 0
	v_pk_add_f32 v[202:203], v[202:203], 1.0 op_sel_hi:[1,0]
	v_pk_add_f32 v[204:205], v[204:205], 1.0 op_sel_hi:[1,0]
	v_pk_add_f32 v[206:207], v[206:207], 1.0 op_sel_hi:[1,0]
	v_rcp_f32_e32 v202, v202
	v_rcp_f32_e32 v203, v203
	v_rcp_f32_e32 v204, v204
	v_rcp_f32_e32 v205, v205
	v_rcp_f32_e32 v206, v206
	v_rcp_f32_e32 v207, v207
	s_nop 0
	v_pk_mul_f32 v[214:215], v[214:215], v[202:203]
	v_pk_mul_f32 v[216:217], v[216:217], v[204:205]
	v_pk_mul_f32 v[236:237], v[236:237], v[206:207]
	v_cvt_pk_bf16_f32 v164, v214, v215
	v_cvt_pk_bf16_f32 v168, v216, v217
	v_cvt_pk_bf16_f32 v172, v236, v237
	v_lshlrev_b32_e32 v202, 16, v165
	v_and_b32_e32 v203, 0xffff0000, v165
	v_lshlrev_b32_e32 v204, 16, v169
	v_and_b32_e32 v205, 0xffff0000, v169
	v_lshlrev_b32_e32 v206, 16, v173
	v_and_b32_e32 v207, 0xffff0000, v173
	v_lshlrev_b32_e32 v208, 16, v177
	v_and_b32_e32 v209, 0xffff0000, v177
	v_lshlrev_b32_e32 v210, 16, v181
	v_and_b32_e32 v211, 0xffff0000, v181
	v_lshlrev_b32_e32 v212, 16, v185
	v_and_b32_e32 v213, 0xffff0000, v185
	v_pk_fma_f32 v[214:215], v[14:15], v[202:203], v[6:7]
	v_pk_fma_f32 v[216:217], v[14:15], v[204:205], v[6:7]
	v_pk_fma_f32 v[236:237], v[14:15], v[206:207], v[6:7]
	v_pk_fma_f32 v[214:215], v[22:23], v[204:205], v[214:215]
	v_pk_fma_f32 v[216:217], v[22:23], v[206:207], v[216:217]
	v_pk_fma_f32 v[236:237], v[22:23], v[208:209], v[236:237]
	v_pk_fma_f32 v[214:215], v[30:31], v[206:207], v[214:215]
	v_pk_fma_f32 v[216:217], v[30:31], v[208:209], v[216:217]
	v_pk_fma_f32 v[236:237], v[30:31], v[210:211], v[236:237]
	v_pk_fma_f32 v[214:215], v[38:39], v[208:209], v[214:215]
	v_pk_fma_f32 v[216:217], v[38:39], v[210:211], v[216:217]
	v_pk_fma_f32 v[236:237], v[38:39], v[212:213], v[236:237]
	v_pk_mul_f32 v[202:203], v[214:215], s[42:43]
	v_pk_mul_f32 v[204:205], v[216:217], s[42:43]
	v_pk_mul_f32 v[206:207], v[236:237], s[42:43]
	v_exp_f32_e32 v202, v202
	v_exp_f32_e32 v203, v203
	v_exp_f32_e32 v204, v204
	v_exp_f32_e32 v205, v205
	v_exp_f32_e32 v206, v206
	v_exp_f32_e32 v207, v207
	s_nop 0
	v_pk_add_f32 v[202:203], v[202:203], 1.0 op_sel_hi:[1,0]
	v_pk_add_f32 v[204:205], v[204:205], 1.0 op_sel_hi:[1,0]
	v_pk_add_f32 v[206:207], v[206:207], 1.0 op_sel_hi:[1,0]
	v_rcp_f32_e32 v202, v202
	v_rcp_f32_e32 v203, v203
	v_rcp_f32_e32 v204, v204
	v_rcp_f32_e32 v205, v205
	v_rcp_f32_e32 v206, v206
	v_rcp_f32_e32 v207, v207
	s_nop 0
	v_pk_mul_f32 v[214:215], v[214:215], v[202:203]
	v_pk_mul_f32 v[216:217], v[216:217], v[204:205]
	v_pk_mul_f32 v[236:237], v[236:237], v[206:207]
	v_cvt_pk_bf16_f32 v165, v214, v215
	v_cvt_pk_bf16_f32 v169, v216, v217
	v_cvt_pk_bf16_f32 v173, v236, v237
	v_lshlrev_b32_e32 v202, 16, v166
	v_and_b32_e32 v203, 0xffff0000, v166
	v_lshlrev_b32_e32 v204, 16, v170
	v_and_b32_e32 v205, 0xffff0000, v170
	v_lshlrev_b32_e32 v206, 16, v174
	v_and_b32_e32 v207, 0xffff0000, v174
	v_lshlrev_b32_e32 v208, 16, v178
	v_and_b32_e32 v209, 0xffff0000, v178
	v_lshlrev_b32_e32 v210, 16, v182
	v_and_b32_e32 v211, 0xffff0000, v182
	v_lshlrev_b32_e32 v212, 16, v186
	v_and_b32_e32 v213, 0xffff0000, v186
	v_pk_fma_f32 v[214:215], v[16:17], v[202:203], v[8:9]
	v_pk_fma_f32 v[216:217], v[16:17], v[204:205], v[8:9]
	v_pk_fma_f32 v[236:237], v[16:17], v[206:207], v[8:9]
	v_pk_fma_f32 v[214:215], v[24:25], v[204:205], v[214:215]
	v_pk_fma_f32 v[216:217], v[24:25], v[206:207], v[216:217]
	v_pk_fma_f32 v[236:237], v[24:25], v[208:209], v[236:237]
	v_pk_fma_f32 v[214:215], v[32:33], v[206:207], v[214:215]
	v_pk_fma_f32 v[216:217], v[32:33], v[208:209], v[216:217]
	v_pk_fma_f32 v[236:237], v[32:33], v[210:211], v[236:237]
	v_pk_fma_f32 v[214:215], v[40:41], v[208:209], v[214:215]
	v_pk_fma_f32 v[216:217], v[40:41], v[210:211], v[216:217]
	v_pk_fma_f32 v[236:237], v[40:41], v[212:213], v[236:237]
	v_pk_mul_f32 v[202:203], v[214:215], s[42:43]
	v_pk_mul_f32 v[204:205], v[216:217], s[42:43]
	v_pk_mul_f32 v[206:207], v[236:237], s[42:43]
	v_exp_f32_e32 v202, v202
	v_exp_f32_e32 v203, v203
	v_exp_f32_e32 v204, v204
	v_exp_f32_e32 v205, v205
	v_exp_f32_e32 v206, v206
	v_exp_f32_e32 v207, v207
	s_nop 0
	v_pk_add_f32 v[202:203], v[202:203], 1.0 op_sel_hi:[1,0]
	v_pk_add_f32 v[204:205], v[204:205], 1.0 op_sel_hi:[1,0]
	v_pk_add_f32 v[206:207], v[206:207], 1.0 op_sel_hi:[1,0]
	v_rcp_f32_e32 v202, v202
	v_rcp_f32_e32 v203, v203
	v_rcp_f32_e32 v204, v204
	v_rcp_f32_e32 v205, v205
	v_rcp_f32_e32 v206, v206
	v_rcp_f32_e32 v207, v207
	s_nop 0
	v_pk_mul_f32 v[214:215], v[214:215], v[202:203]
	v_pk_mul_f32 v[216:217], v[216:217], v[204:205]
	v_pk_mul_f32 v[236:237], v[236:237], v[206:207]
	v_cvt_pk_bf16_f32 v166, v214, v215
	v_cvt_pk_bf16_f32 v170, v216, v217
	v_cvt_pk_bf16_f32 v174, v236, v237
	v_lshlrev_b32_e32 v202, 16, v167
	v_and_b32_e32 v203, 0xffff0000, v167
	v_lshlrev_b32_e32 v204, 16, v171
	v_and_b32_e32 v205, 0xffff0000, v171
	v_lshlrev_b32_e32 v206, 16, v175
	v_and_b32_e32 v207, 0xffff0000, v175
	v_lshlrev_b32_e32 v208, 16, v179
	v_and_b32_e32 v209, 0xffff0000, v179
	v_lshlrev_b32_e32 v210, 16, v183
	v_and_b32_e32 v211, 0xffff0000, v183
	v_lshlrev_b32_e32 v212, 16, v187
	v_and_b32_e32 v213, 0xffff0000, v187
	v_pk_fma_f32 v[214:215], v[18:19], v[202:203], v[10:11]
	v_pk_fma_f32 v[216:217], v[18:19], v[204:205], v[10:11]
	v_pk_fma_f32 v[236:237], v[18:19], v[206:207], v[10:11]
	v_pk_fma_f32 v[214:215], v[26:27], v[204:205], v[214:215]
	v_pk_fma_f32 v[216:217], v[26:27], v[206:207], v[216:217]
	v_pk_fma_f32 v[236:237], v[26:27], v[208:209], v[236:237]
	v_pk_fma_f32 v[214:215], v[34:35], v[206:207], v[214:215]
	v_pk_fma_f32 v[216:217], v[34:35], v[208:209], v[216:217]
	v_pk_fma_f32 v[236:237], v[34:35], v[210:211], v[236:237]
	v_pk_fma_f32 v[214:215], v[42:43], v[208:209], v[214:215]
	v_pk_fma_f32 v[216:217], v[42:43], v[210:211], v[216:217]
	v_pk_fma_f32 v[236:237], v[42:43], v[212:213], v[236:237]
	v_pk_mul_f32 v[202:203], v[214:215], s[42:43]
	v_pk_mul_f32 v[204:205], v[216:217], s[42:43]
	v_pk_mul_f32 v[206:207], v[236:237], s[42:43]
	v_exp_f32_e32 v202, v202
	v_exp_f32_e32 v203, v203
	v_exp_f32_e32 v204, v204
	v_exp_f32_e32 v205, v205
	v_exp_f32_e32 v206, v206
	v_exp_f32_e32 v207, v207
	s_nop 0
	v_pk_add_f32 v[202:203], v[202:203], 1.0 op_sel_hi:[1,0]
	v_pk_add_f32 v[204:205], v[204:205], 1.0 op_sel_hi:[1,0]
	v_pk_add_f32 v[206:207], v[206:207], 1.0 op_sel_hi:[1,0]
	v_rcp_f32_e32 v202, v202
	v_rcp_f32_e32 v203, v203
	v_rcp_f32_e32 v204, v204
	v_rcp_f32_e32 v205, v205
	v_rcp_f32_e32 v206, v206
	v_rcp_f32_e32 v207, v207
	s_nop 0
	v_pk_mul_f32 v[214:215], v[214:215], v[202:203]
	v_pk_mul_f32 v[216:217], v[216:217], v[204:205]
	v_pk_mul_f32 v[236:237], v[236:237], v[206:207]
	v_cvt_pk_bf16_f32 v167, v214, v215
	v_cvt_pk_bf16_f32 v171, v216, v217
	v_cvt_pk_bf16_f32 v175, v236, v237
	v_add_u32_e32 v0, 60, v238
	v_cmp_eq_u32_e32 vcc, 64, v0
	v_add_u32_e32 v1, s22, v0
	v_mov_b32_e32 v2, 0x200
	v_cndmask_b32_e32 v1, v1, v2, vcc
	v_cmp_gt_u32_e32 vcc, 65, v0
	s_and_saveexec_b64 s[38:39], vcc
	v_add_u32_e32 v2, 0x1000, v240
	v_mad_u32_u24 v1, v1, s23, v2
	global_store_dwordx4 v1, v[164:167], s[96:97]
	v_add_u32_e32 v1, 0x3400, v1
	global_store_dwordx4 v1, v[168:171], s[96:97]
	v_add_u32_e32 v1, 0x3400, v1
	global_store_dwordx4 v1, v[172:175], s[96:97]
	s_waitcnt vmcnt(0)

.LBB0_349:
	s_waitcnt vmcnt(5)
	v_cndmask_b32_e64 v4, 0, v4, s[0:1]
	v_cndmask_b32_e64 v5, 0, v5, s[0:1]
	v_cndmask_b32_e64 v6, 0, v6, s[0:1]
	v_cndmask_b32_e64 v7, 0, v7, s[0:1]
	s_waitcnt vmcnt(4)
	v_cndmask_b32_e64 v8, 0, v8, s[0:1]
	v_cndmask_b32_e64 v9, 0, v9, s[0:1]
	v_cndmask_b32_e64 v10, 0, v10, s[0:1]
	v_cndmask_b32_e64 v11, 0, v11, s[0:1]
	s_waitcnt vmcnt(3)
	v_cndmask_b32_e64 v12, 0, v12, s[0:1]
	v_cndmask_b32_e64 v13, 0, v13, s[0:1]
	v_cndmask_b32_e64 v14, 0, v14, s[0:1]
	v_cndmask_b32_e64 v15, 0, v15, s[0:1]
	s_waitcnt vmcnt(2)
	v_cndmask_b32_e64 v20, 0, v16, s[0:1]
	v_cndmask_b32_e64 v21, 0, v17, s[0:1]
	v_cndmask_b32_e64 v22, 0, v18, s[0:1]
	v_cndmask_b32_e64 v23, 0, v19, s[0:1]
	s_or_b32 s37, s85, 64
	v_readlane_b32 s0, v252, 52
	s_add_u32 s62, s0, s72
	v_readlane_b32 s0, v254, 27
	v_cmp_lt_i32_e32 vcc, -5, v48
	v_readlane_b32 s1, v252, 53
	v_mov_b32_e32 v2, s0
	v_cndmask_b32_e32 v17, 0, v25, vcc
	v_cndmask_b32_e32 v25, 0, v29, vcc
	v_cndmask_b32_e32 v29, 0, v33, vcc
	v_cndmask_b32_e32 v33, 0, v37, vcc
	v_cndmask_b32_e64 v2, 0, v2, s[38:39]
	s_movk_i32 s0, 0x440
	v_or_b32_e32 v37, 1, v50
	s_movk_i32 s3, 0x110
	v_cndmask_b32_e64 v58, 0, v40, s[40:41]
	v_cndmask_b32_e64 v59, 0, v41, s[40:41]
	s_addc_u32 s63, s1, 0
	v_mad_u64_u32 v[40:41], s[0:1], v48, s0, v[2:3]
	v_mad_u64_u32 v[70:71], s[0:1], v37, s3, v[2:3]
	s_movk_i32 s0, 0x6800
	s_nop 0
	v_mul_lo_u32 v72, v48, s0
	s_movk_i32 s0, 0x120
	v_cndmask_b32_e32 v16, 0, v24, vcc
	v_cndmask_b32_e32 v24, 0, v28, vcc
	v_cndmask_b32_e32 v28, 0, v32, vcc
	v_cndmask_b32_e32 v32, 0, v36, vcc
	v_and_b32_e32 v36, 15, v51
	v_lshl_or_b32 v64, v94, 2, s23
	s_movk_i32 s2, 0x1a00
	v_mul_lo_u32 v96, v49, s0
	v_or_b32_e32 v2, 1, v55
	s_add_i32 s0, 0, 0x1a400
	s_add_i32 s1, 0, 0x1a600
	s_add_i32 s23, 0, 0x18000
	s_movk_i32 s25, 0x480
	v_lshl_or_b32 v62, v36, 3, v54
	v_lshlrev_b32_e32 v95, 4, v36
	v_mul_lo_u32 v97, v2, s71
	v_mul_lo_u32 v82, v2, s2
	s_cmp_lt_u32 s30, 32
	v_bitop3_b32 v2, v48, v1, 14 bitop3:0x78
	v_mad_u32_u24 v102, v36, s25, 0
	v_lshlrev_b32_e32 v36, 2, v65
	v_readlane_b32 s42, v252, 44
	v_cndmask_b32_e32 v18, 0, v26, vcc
	v_cndmask_b32_e32 v19, 0, v27, vcc
	v_cndmask_b32_e32 v26, 0, v30, vcc
	v_cndmask_b32_e32 v27, 0, v31, vcc
	v_cndmask_b32_e32 v30, 0, v34, vcc
	v_cndmask_b32_e32 v31, 0, v35, vcc
	v_cndmask_b32_e32 v34, 0, v38, vcc
	v_cndmask_b32_e32 v35, 0, v39, vcc
	v_cmp_lt_i32_e32 vcc, -9, v49
	s_cselect_b64 s[64:65], -1, 0
	v_lshlrev_b32_e32 v100, 3, v2
	v_readlane_b32 s43, v252, 45
	s_add_u32 s66, s42, s72
	v_or_b32_e32 v2, 0x100, v36
	v_cndmask_b32_e32 v69, 0, v47, vcc
	s_addc_u32 s67, s43, 0
	v_add_u32_e32 v104, s0, v2
	v_add_u32_e32 v105, s1, v2
	v_or_b32_e32 v47, s27, v94
	v_mov_b32_e32 v2, s23
	s_lshl_b32 s22, s22, 1
	v_lshrrev_b32_e32 v38, 4, v65
	v_mad_u32_u24 v108, v47, s71, v2
	v_lshrrev_b32_e32 v2, 3, v94
	s_and_b32 s22, s22, 6
	v_or_b32_e32 v51, s22, v2
	v_bitop3_b32 v2, s22, v38, v2 bitop3:0x36
	s_lshl_b32 s22, s21, 6
	v_lshlrev_b32_e32 v54, 4, v2
	v_or_b32_e32 v2, s22, v94
	v_mul_lo_u32 v2, v2, s71
	v_cndmask_b32_e64 v61, 0, v43, s[40:41]
	v_lshlrev_b32_e32 v39, 2, v55
	v_lshlrev_b32_e32 v43, 1, v1
	v_add_u32_e32 v55, 0, v2
	v_lshlrev_b32_e32 v2, 3, v38
	v_lshl_or_b32 v38, v38, 2, s27
	v_bitop3_b32 v43, v43, v49, 28 bitop3:0x6c
	v_or_b32_e32 v110, 2, v38
	v_mul_lo_u32 v74, v37, s2
	v_lshlrev_b32_e32 v37, 3, v94
	v_readlane_b32 s4, v254, 28
	v_lshlrev_b32_e32 v43, 2, v43
	v_readlane_b32 s2, v254, 30
	v_mad_u32_u24 v106, v47, s3, 0
	v_and_b32_e32 v107, 48, v1
	v_mul_lo_u32 v48, v86, s3
	s_lshl_b32 s25, s20, 6
	v_cmp_gt_i32_e64 s[46:47], v110, v86
	v_or_b32_e32 v110, 3, v38
	v_readlane_b32 s3, v254, 31
	v_lshlrev_b32_e32 v51, 4, v51
	s_lshl_b32 s20, s20, 8
	v_cndmask_b32_e32 v67, 0, v45, vcc
	v_add_u32_e32 v71, s4, v37
	v_readlane_b32 s5, v254, 29
	v_add_u32_e32 v45, s23, v43
	v_add_u32_e32 v101, s2, v36
	s_and_b32 s23, s22, 64
	v_lshlrev_b32_e32 v120, 2, v86
	v_cmp_gt_i32_e64 s[42:43], v38, v86
	v_cmp_lt_i32_e64 s[44:45], v38, v86
	v_cmp_gt_i32_e64 s[48:49], v110, v86
	v_mul_lo_u32 v150, v86, s71
	s_add_i32 s27, s26, s3
	v_lshlrev_b32_e32 v121, 2, v87
	v_cmp_gt_i32_e64 s[50:51], v38, v87
	v_cmp_lt_i32_e64 s[52:53], v38, v87
	v_add_u32_e32 v87, 14, v86
	v_add_u32_e32 v86, 13, v86
	v_bitop3_b32 v111, v51, v107, 64 bitop3:0x1e
	v_add_u32_e32 v151, s3, v107
	v_bitop3_b32 v113, v51, v1, 48 bitop3:0x78
	v_lshl_add_u32 v51, s21, 7, v106
	s_add_i32 s21, s26, s4
	s_add_i32 s20, s2, s20
	v_readlane_b32 s2, v254, 32
	v_readlane_b32 s3, v254, 33
	v_readlane_b32 s4, v254, 35
	v_cndmask_b32_e64 v60, 0, v42, s[40:41]
	v_cmp_gt_i32_e64 s[40:41], 64, v1
	v_or_b32_e32 v50, 64, v107
	v_bitop3_b32 v91, s23, v1, 48 bitop3:0x72
	v_cmp_gt_i32_e64 s[54:55], v38, v87
	v_cmp_gt_i32_e64 s[56:57], v38, v86
	v_add_u32_e32 v38, 0x900, v150
	v_mov_b32_e32 v86, s5
	v_add_u32_e32 v116, s3, v39
	v_readlane_b32 s3, v254, 34
	v_mov_b32_e32 v1, s4
	s_add_i32 s26, s26, s2
	v_cndmask_b32_e32 v66, 0, v44, vcc
	v_cndmask_b32_e32 v68, 0, v46, vcc
	v_add_u32_e32 v41, 0x110, v70
	v_add_u32_e32 v42, 0x220, v70
	v_add_u32_e32 v98, s0, v39
	v_add_u32_e32 v99, s1, v39
	v_add_u32_e32 v44, s5, v43
	v_mul_u32_u24_e32 v46, 0x240, v94
	v_mul_lo_u32 v80, v49, s29
	v_add_u32_e32 v49, 0, v107
	v_and_b32_e32 v92, 48, v65
	v_add_u32_e32 v145, s27, v38
	v_bitop3_b32 v147, s23, v50, 16 bitop3:0x36
	v_bitop3_b32 v148, s23, v50, 32 bitop3:0x36
	v_bitop3_b32 v50, s23, v50, 48 bitop3:0x36
	v_mad_u32_u24 v112, v47, s71, v86
	v_add_u32_e32 v129, s21, v38
	v_add_u32_e32 v117, s3, v39
	v_add_u32_e32 v43, s4, v43
	v_mad_u32_u24 v122, v47, s71, v1
	v_add_u32_e32 v47, s26, v150
	v_add_u32_e32 v133, s26, v38
	v_mov_b32_e32 v38, v3
	v_mov_b32_e32 v39, v3
	v_add_u32_e32 v76, 0x1a00, v74
	v_add_u32_e32 v78, 0x3400, v74
	v_add_u32_e32 v88, s23, v55
	v_bitop3_b32 v89, s23, v107, 16 bitop3:0x36
	v_bitop3_b32 v90, s23, v107, 32 bitop3:0x36
	v_add_u32_e32 v93, s1, v92
	v_add_u32_e32 v144, s27, v150
	v_bitop3_b32 v146, s22, v107, 64 bitop3:0x4e
	v_add_u32_e32 v128, s21, v150
	v_lshl_add_u64 v[86:87], s[74:75], 0, v[2:3]
	s_add_i32 s74, s24, s85
	v_add_u32_e32 v115, s2, v37
	v_add_u32_e32 v118, s0, v36
	v_add_u32_e32 v119, s1, v36
	v_add_u32_e32 v92, s3, v92
	v_mov_b32_e32 v36, v3
	v_mov_b32_e32 v37, v3
	v_add_u32_e32 v126, v44, v46
	v_add_u32_e32 v130, v43, v46
	v_add_u32_e32 v132, v47, v2
	v_add_u32_e32 v134, v40, v95
	v_add_u32_e32 v135, v41, v95
	v_add_u32_e32 v136, v42, v95
	v_add_u32_e32 v137, v45, v46
	v_add_u32_e32 v138, v49, v48
	v_add_u32_e32 v149, v55, v50
	v_add_u32_e32 v150, v151, v150
	v_add_u32_e32 v151, v51, v2
	v_mov_b64_e32 v[46:47], v[38:39]
	v_mov_b64_e32 v[42:43], v[38:39]
	v_mov_b64_e32 v[50:51], v[38:39]
	s_mov_b32 s36, 0
	s_mov_b32 s78, 1
	v_ashrrev_i32_e32 v73, 31, v72
	v_ashrrev_i32_e32 v75, 31, v74
	v_ashrrev_i32_e32 v77, 31, v76
	v_ashrrev_i32_e32 v79, 31, v78
	v_ashrrev_i32_e32 v81, 31, v80
	v_ashrrev_i32_e32 v83, 31, v82
	v_add_u32_e32 v103, 0xffffff90, v65
	v_add_u32_e32 v109, s1, v120
	v_add_u32_e32 v110, s1, v121
	v_cmp_gt_u32_e64 s[58:59], 16, v65
	v_add_u32_e32 v114, s20, v120
	v_add_u32_e32 v120, s3, v120
	v_add_u32_e32 v121, s3, v121
	s_add_i32 s75, s74, 16
	v_mov_b32_e32 v1, v0
	v_subrev_u32_e32 v123, 48, v65
	v_add_u32_e32 v124, s24, v94
	v_add_u32_e32 v125, s74, v94
	s_xor_b64 s[82:83], s[60:61], -1
	v_add_u32_e32 v127, s25, v93
	v_add_u32_e32 v128, v128, v2
	v_add_u32_e32 v129, v129, v2
	v_add_u32_e32 v131, s25, v92
	v_add_u32_e32 v133, v133, v2
	v_add_u32_e32 v139, v108, v54
	v_add_u32_e32 v140, v88, v107
	v_add_u32_e32 v141, v55, v89
	v_add_u32_e32 v142, v55, v90
	v_add_u32_e32 v143, v55, v91
	v_add_u32_e32 v144, v144, v2
	v_add_u32_e32 v145, v145, v2
	v_add_u32_e32 v146, v55, v146
	v_add_u32_e32 v147, v55, v147
	v_add_u32_e32 v148, v55, v148
	v_mov_b64_e32 v[44:45], v[36:37]
	v_mov_b64_e32 v[40:41], v[36:37]
	v_mov_b64_e32 v[48:49], v[36:37]
	s_mov_b32 s81, 0
	s_waitcnt lgkmcnt(0)
	s_barrier
	s_branch .LBB0_352
